# gate epilogues (P5, P13): sigmoid of the first 8 groups runs under the latency of the x1/ple loads, group g+8's sigmoid rides with group g
# baseline (speedup 1.0000x reference)
.LBB0_878:
	ds_read_b128 v[140:143], v149
	ds_read_b128 v[152:155], v149 offset:1024
	ds_read_b128 v[156:159], v149 offset:2048
	ds_read_b128 v[160:163], v149 offset:3072
	s_add_u32 s36, s22, 0xfffc0080
	s_addc_u32 s37, s23, -1
	s_cmp_eq_u32 s59, 12
	s_cselect_b32 s39, s11, s37
	s_cselect_b32 s38, s15, s36
	s_cselect_b32 s37, s49, s58
	s_cselect_b32 s36, s56, s57
	v_lshl_add_u64 v[144:145], s[22:23], 0, v[132:133]
	s_add_i32 m0, s21, 0xc000
	ds_read_b128 v[164:167], v150
	ds_read_b128 v[168:171], v150 offset:1024
	ds_read_b128 v[172:175], v150 offset:2048
	ds_read_b128 v[176:179], v150 offset:3072
	ds_read_b128 v[180:183], v150 offset:4096
	ds_read_b128 v[184:187], v150 offset:5120
	ds_read_b128 v[188:191], v150 offset:6144
	ds_read_b128 v[192:195], v150 offset:7168
	global_load_lds_dwordx4 v[144:145], off
	v_lshl_add_u64 v[144:145], s[22:23], 0, v[134:135]
	s_add_i32 m0, s21, 0xe000
	s_nop 0
	global_load_lds_dwordx4 v[144:145], off
	s_waitcnt lgkmcnt(8)
	s_barrier
	s_waitcnt lgkmcnt(0)
	s_setprio 1
	s_waitcnt lgkmcnt(0)
	v_mfma_f32_16x16x32_bf16 v[124:127], v[140:143], v[164:167], v[124:127]
	v_mfma_f32_16x16x32_bf16 v[120:123], v[156:159], v[164:167], v[120:123]
	v_mfma_f32_16x16x32_bf16 v[108:111], v[140:143], v[172:175], v[108:111]
	v_mfma_f32_16x16x32_bf16 v[104:107], v[156:159], v[172:175], v[104:107]
	v_mfma_f32_16x16x32_bf16 v[92:95], v[140:143], v[180:183], v[92:95]
	v_mfma_f32_16x16x32_bf16 v[88:91], v[156:159], v[180:183], v[88:91]
	v_mfma_f32_16x16x32_bf16 v[76:79], v[140:143], v[188:191], v[76:79]
	v_mfma_f32_16x16x32_bf16 v[72:75], v[156:159], v[188:191], v[72:75]
	v_mfma_f32_16x16x32_bf16 v[124:127], v[152:155], v[168:171], v[124:127]
	v_mfma_f32_16x16x32_bf16 v[120:123], v[160:163], v[168:171], v[120:123]
	v_mfma_f32_16x16x32_bf16 v[108:111], v[152:155], v[176:179], v[108:111]
	v_mfma_f32_16x16x32_bf16 v[104:107], v[160:163], v[176:179], v[104:107]
	v_mfma_f32_16x16x32_bf16 v[92:95], v[152:155], v[184:187], v[92:95]
	v_mfma_f32_16x16x32_bf16 v[88:91], v[160:163], v[184:187], v[88:91]
	v_mfma_f32_16x16x32_bf16 v[76:79], v[152:155], v[192:195], v[76:79]
	v_mfma_f32_16x16x32_bf16 v[72:75], v[160:163], v[192:195], v[72:75]
	s_setprio 0
	s_barrier
	s_add_i32 s60, s42, s25
	v_lshl_add_u64 v[144:145], s[36:37], 0, v[130:131]
	s_mov_b32 m0, s60
	ds_read_b128 v[200:203], v151
	ds_read_b128 v[204:207], v151 offset:1024
	ds_read_b128 v[208:211], v151 offset:2048
	ds_read_b128 v[212:215], v151 offset:3072
	global_load_lds_dwordx4 v[144:145], off
	v_lshl_add_u64 v[196:197], s[36:37], 0, v[128:129]
	s_add_i32 m0, s60, 0x2000
	s_nop 0
	global_load_lds_dwordx4 v[196:197], off
	s_barrier
	s_waitcnt lgkmcnt(0)
	s_setprio 1
	s_waitcnt lgkmcnt(0)
	v_mfma_f32_16x16x32_bf16 v[116:119], v[200:203], v[164:167], v[116:119]
	v_mfma_f32_16x16x32_bf16 v[112:115], v[208:211], v[164:167], v[112:115]
	v_mfma_f32_16x16x32_bf16 v[100:103], v[200:203], v[172:175], v[100:103]
	v_mfma_f32_16x16x32_bf16 v[96:99], v[208:211], v[172:175], v[96:99]
	v_mfma_f32_16x16x32_bf16 v[84:87], v[200:203], v[180:183], v[84:87]
	v_mfma_f32_16x16x32_bf16 v[80:83], v[208:211], v[180:183], v[80:83]
	v_mfma_f32_16x16x32_bf16 v[68:71], v[200:203], v[188:191], v[68:71]
	v_mfma_f32_16x16x32_bf16 v[64:67], v[208:211], v[188:191], v[64:67]
	v_mfma_f32_16x16x32_bf16 v[116:119], v[204:207], v[168:171], v[116:119]
	v_mfma_f32_16x16x32_bf16 v[112:115], v[212:215], v[168:171], v[112:115]
	v_mfma_f32_16x16x32_bf16 v[100:103], v[204:207], v[176:179], v[100:103]
	v_mfma_f32_16x16x32_bf16 v[96:99], v[212:215], v[176:179], v[96:99]
	v_mfma_f32_16x16x32_bf16 v[84:87], v[204:207], v[184:187], v[84:87]
	v_mfma_f32_16x16x32_bf16 v[80:83], v[212:215], v[184:187], v[80:83]
	v_mfma_f32_16x16x32_bf16 v[68:71], v[204:207], v[192:195], v[68:71]
	v_mfma_f32_16x16x32_bf16 v[64:67], v[212:215], v[192:195], v[64:67]
	s_setprio 0
	s_mov_b32 m0, s21
	v_lshl_add_u64 v[216:217], s[38:39], 0, v[130:131]
	s_barrier
	ds_read_b128 v[164:167], v150 offset:16384
	ds_read_b128 v[168:171], v150 offset:17408
	ds_read_b128 v[172:175], v150 offset:18432
	ds_read_b128 v[176:179], v150 offset:19456
	ds_read_b128 v[180:183], v150 offset:20480
	ds_read_b128 v[184:187], v150 offset:21504
	ds_read_b128 v[188:191], v150 offset:22528
	ds_read_b128 v[192:195], v150 offset:23552
	global_load_lds_dwordx4 v[216:217], off
	v_lshl_add_u64 v[218:219], s[38:39], 0, v[128:129]
	s_mov_b32 m0, s26
	s_nop 0
	global_load_lds_dwordx4 v[218:219], off
	s_barrier
	s_waitcnt lgkmcnt(0)
	s_setprio 1
	s_waitcnt lgkmcnt(0)
	v_mfma_f32_16x16x32_bf16 v[60:63], v[140:143], v[164:167], v[60:63]
	v_mfma_f32_16x16x32_bf16 v[56:59], v[156:159], v[164:167], v[56:59]
	v_mfma_f32_16x16x32_bf16 v[44:47], v[140:143], v[172:175], v[44:47]
	v_mfma_f32_16x16x32_bf16 v[40:43], v[156:159], v[172:175], v[40:43]
	v_mfma_f32_16x16x32_bf16 v[28:31], v[140:143], v[180:183], v[28:31]
	v_mfma_f32_16x16x32_bf16 v[24:27], v[156:159], v[180:183], v[24:27]
	v_mfma_f32_16x16x32_bf16 v[12:15], v[140:143], v[188:191], v[12:15]
	v_mfma_f32_16x16x32_bf16 v[8:11], v[156:159], v[188:191], v[8:11]
	v_mfma_f32_16x16x32_bf16 v[60:63], v[152:155], v[168:171], v[60:63]
	v_mfma_f32_16x16x32_bf16 v[56:59], v[160:163], v[168:171], v[56:59]
	v_mfma_f32_16x16x32_bf16 v[44:47], v[152:155], v[176:179], v[44:47]
	v_mfma_f32_16x16x32_bf16 v[40:43], v[160:163], v[176:179], v[40:43]
	v_mfma_f32_16x16x32_bf16 v[28:31], v[152:155], v[184:187], v[28:31]
	v_mfma_f32_16x16x32_bf16 v[24:27], v[160:163], v[184:187], v[24:27]
	v_mfma_f32_16x16x32_bf16 v[12:15], v[152:155], v[192:195], v[12:15]
	v_mfma_f32_16x16x32_bf16 v[8:11], v[160:163], v[192:195], v[8:11]
	s_setprio 0
	s_barrier
	s_add_u32 s60, s36, 0x40000
	s_addc_u32 s61, s37, 0
	s_add_i32 s62, s43, s25
	v_lshl_add_u64 v[140:141], s[60:61], 0, v[130:131]
	s_mov_b32 m0, s62
	s_nop 0
	global_load_lds_dwordx4 v[140:141], off
	v_lshl_add_u64 v[140:141], s[60:61], 0, v[128:129]
	s_add_i32 m0, s62, 0x2000
	s_nop 0
	global_load_lds_dwordx4 v[140:141], off
	s_waitcnt vmcnt(6)
	s_barrier
	s_setprio 1
	v_mfma_f32_16x16x32_bf16 v[52:55], v[200:203], v[164:167], v[52:55]
	v_mfma_f32_16x16x32_bf16 v[48:51], v[208:211], v[164:167], v[48:51]
	v_mfma_f32_16x16x32_bf16 v[36:39], v[200:203], v[172:175], v[36:39]
	v_mfma_f32_16x16x32_bf16 v[32:35], v[208:211], v[172:175], v[32:35]
	v_mfma_f32_16x16x32_bf16 v[20:23], v[200:203], v[180:183], v[20:23]
	v_mfma_f32_16x16x32_bf16 v[16:19], v[208:211], v[180:183], v[16:19]
	v_mfma_f32_16x16x32_bf16 v[4:7], v[200:203], v[188:191], v[4:7]
	v_mfma_f32_16x16x32_bf16 v[0:3], v[208:211], v[188:191], v[0:3]
	v_mfma_f32_16x16x32_bf16 v[52:55], v[204:207], v[168:171], v[52:55]
	v_mfma_f32_16x16x32_bf16 v[48:51], v[212:215], v[168:171], v[48:51]
	v_mfma_f32_16x16x32_bf16 v[36:39], v[204:207], v[176:179], v[36:39]
	v_mfma_f32_16x16x32_bf16 v[32:35], v[212:215], v[176:179], v[32:35]
	v_mfma_f32_16x16x32_bf16 v[20:23], v[204:207], v[184:187], v[20:23]
	v_mfma_f32_16x16x32_bf16 v[16:19], v[212:215], v[184:187], v[16:19]
	v_mfma_f32_16x16x32_bf16 v[4:7], v[204:207], v[192:195], v[4:7]
	v_mfma_f32_16x16x32_bf16 v[0:3], v[212:215], v[192:195], v[0:3]
	s_setprio 0
	s_add_i32 s60, 0, 0x18000
	v_add_u32_e32 v160, s60, v147
	s_barrier
	ds_read_b128 v[140:143], v160
	ds_read_b128 v[152:155], v160 offset:1024
	ds_read_b128 v[156:159], v160 offset:2048
	ds_read_b128 v[160:163], v160 offset:3072
	s_add_u32 s38, s38, 0x40000
	s_addc_u32 s39, s39, 0
	s_mov_b32 m0, s27
	v_lshl_add_u64 v[200:201], s[38:39], 0, v[130:131]
	ds_read_b128 v[164:167], v150 offset:32768
	ds_read_b128 v[168:171], v150 offset:33792
	ds_read_b128 v[172:175], v150 offset:34816
	ds_read_b128 v[176:179], v150 offset:35840
	ds_read_b128 v[180:183], v150 offset:36864
	ds_read_b128 v[184:187], v150 offset:37888
	ds_read_b128 v[188:191], v150 offset:38912
	ds_read_b128 v[192:195], v150 offset:39936
	global_load_lds_dwordx4 v[200:201], off
	v_lshl_add_u64 v[200:201], s[38:39], 0, v[128:129]
	s_mov_b32 m0, s28
	s_nop 0
	global_load_lds_dwordx4 v[200:201], off
	s_waitcnt lgkmcnt(8)
	s_barrier
	s_waitcnt lgkmcnt(0)
	s_setprio 1
	s_waitcnt lgkmcnt(0)
	v_mfma_f32_16x16x32_bf16 v[124:127], v[140:143], v[164:167], v[124:127]
	v_mfma_f32_16x16x32_bf16 v[120:123], v[156:159], v[164:167], v[120:123]
	v_mfma_f32_16x16x32_bf16 v[108:111], v[140:143], v[172:175], v[108:111]
	v_mfma_f32_16x16x32_bf16 v[104:107], v[156:159], v[172:175], v[104:107]
	v_mfma_f32_16x16x32_bf16 v[92:95], v[140:143], v[180:183], v[92:95]
	v_mfma_f32_16x16x32_bf16 v[88:91], v[156:159], v[180:183], v[88:91]
	v_mfma_f32_16x16x32_bf16 v[76:79], v[140:143], v[188:191], v[76:79]
	v_mfma_f32_16x16x32_bf16 v[72:75], v[156:159], v[188:191], v[72:75]
	v_mfma_f32_16x16x32_bf16 v[124:127], v[152:155], v[168:171], v[124:127]
	v_mfma_f32_16x16x32_bf16 v[120:123], v[160:163], v[168:171], v[120:123]
	v_mfma_f32_16x16x32_bf16 v[108:111], v[152:155], v[176:179], v[108:111]
	v_mfma_f32_16x16x32_bf16 v[104:107], v[160:163], v[176:179], v[104:107]
	v_mfma_f32_16x16x32_bf16 v[92:95], v[152:155], v[184:187], v[92:95]
	v_mfma_f32_16x16x32_bf16 v[88:91], v[160:163], v[184:187], v[88:91]
	v_mfma_f32_16x16x32_bf16 v[76:79], v[152:155], v[192:195], v[76:79]
	v_mfma_f32_16x16x32_bf16 v[72:75], v[160:163], v[192:195], v[72:75]
	s_setprio 0
	s_barrier
	s_add_i32 s38, 0, 0x1c000
	s_add_i32 s39, s60, s25
	v_add_u32_e32 v212, s38, v147
	v_lshl_add_u64 v[144:145], v[144:145], 0, s[8:9]
	s_mov_b32 m0, s39
	ds_read_b128 v[200:203], v212
	ds_read_b128 v[204:207], v212 offset:1024
	ds_read_b128 v[208:211], v212 offset:2048
	ds_read_b128 v[212:215], v212 offset:3072
	global_load_lds_dwordx4 v[144:145], off
	v_lshl_add_u64 v[144:145], v[196:197], 0, s[8:9]
	s_add_i32 m0, s39, 0x2000
	s_nop 0
	global_load_lds_dwordx4 v[144:145], off
	s_barrier
	s_waitcnt lgkmcnt(0)
	s_setprio 1
	s_waitcnt lgkmcnt(0)
	v_mfma_f32_16x16x32_bf16 v[116:119], v[200:203], v[164:167], v[116:119]
	v_mfma_f32_16x16x32_bf16 v[112:115], v[208:211], v[164:167], v[112:115]
	v_mfma_f32_16x16x32_bf16 v[100:103], v[200:203], v[172:175], v[100:103]
	v_mfma_f32_16x16x32_bf16 v[96:99], v[208:211], v[172:175], v[96:99]
	v_mfma_f32_16x16x32_bf16 v[84:87], v[200:203], v[180:183], v[84:87]
	v_mfma_f32_16x16x32_bf16 v[80:83], v[208:211], v[180:183], v[80:83]
	v_mfma_f32_16x16x32_bf16 v[68:71], v[200:203], v[188:191], v[68:71]
	v_mfma_f32_16x16x32_bf16 v[64:67], v[208:211], v[188:191], v[64:67]
	v_mfma_f32_16x16x32_bf16 v[116:119], v[204:207], v[168:171], v[116:119]
	v_mfma_f32_16x16x32_bf16 v[112:115], v[212:215], v[168:171], v[112:115]
	v_mfma_f32_16x16x32_bf16 v[100:103], v[204:207], v[176:179], v[100:103]
	v_mfma_f32_16x16x32_bf16 v[96:99], v[212:215], v[176:179], v[96:99]
	v_mfma_f32_16x16x32_bf16 v[84:87], v[204:207], v[184:187], v[84:87]
	v_mfma_f32_16x16x32_bf16 v[80:83], v[212:215], v[184:187], v[80:83]
	v_mfma_f32_16x16x32_bf16 v[68:71], v[204:207], v[192:195], v[68:71]
	v_mfma_f32_16x16x32_bf16 v[64:67], v[212:215], v[192:195], v[64:67]
	s_setprio 0
	s_mov_b32 m0, s40
	v_lshl_add_u64 v[144:145], v[216:217], 0, s[8:9]
	s_barrier
	ds_read_b128 v[164:167], v150 offset:49152
	ds_read_b128 v[168:171], v150 offset:50176
	ds_read_b128 v[172:175], v150 offset:51200
	ds_read_b128 v[176:179], v150 offset:52224
	ds_read_b128 v[180:183], v150 offset:53248
	ds_read_b128 v[184:187], v150 offset:54272
	ds_read_b128 v[188:191], v150 offset:55296
	ds_read_b128 v[192:195], v150 offset:56320
	global_load_lds_dwordx4 v[144:145], off
	v_lshl_add_u64 v[144:145], v[218:219], 0, s[8:9]
	s_mov_b32 m0, s41
	s_nop 0
	global_load_lds_dwordx4 v[144:145], off
	s_barrier
	s_waitcnt lgkmcnt(0)
	s_setprio 1
	s_waitcnt lgkmcnt(0)
	v_mfma_f32_16x16x32_bf16 v[60:63], v[140:143], v[164:167], v[60:63]
	v_mfma_f32_16x16x32_bf16 v[56:59], v[156:159], v[164:167], v[56:59]
	v_mfma_f32_16x16x32_bf16 v[44:47], v[140:143], v[172:175], v[44:47]
	v_mfma_f32_16x16x32_bf16 v[40:43], v[156:159], v[172:175], v[40:43]
	v_mfma_f32_16x16x32_bf16 v[28:31], v[140:143], v[180:183], v[28:31]
	v_mfma_f32_16x16x32_bf16 v[24:27], v[156:159], v[180:183], v[24:27]
	v_mfma_f32_16x16x32_bf16 v[12:15], v[140:143], v[188:191], v[12:15]
	v_mfma_f32_16x16x32_bf16 v[8:11], v[156:159], v[188:191], v[8:11]
	v_mfma_f32_16x16x32_bf16 v[60:63], v[152:155], v[168:171], v[60:63]
	v_mfma_f32_16x16x32_bf16 v[56:59], v[160:163], v[168:171], v[56:59]
	v_mfma_f32_16x16x32_bf16 v[44:47], v[152:155], v[176:179], v[44:47]
	v_mfma_f32_16x16x32_bf16 v[40:43], v[160:163], v[176:179], v[40:43]
	v_mfma_f32_16x16x32_bf16 v[28:31], v[152:155], v[184:187], v[28:31]
	v_mfma_f32_16x16x32_bf16 v[24:27], v[160:163], v[184:187], v[24:27]
	v_mfma_f32_16x16x32_bf16 v[12:15], v[152:155], v[192:195], v[12:15]
	v_mfma_f32_16x16x32_bf16 v[8:11], v[160:163], v[192:195], v[8:11]
	s_setprio 0
	s_barrier
	s_add_u32 s36, s36, 0x40080
	s_addc_u32 s37, s37, 0
	s_add_i32 s38, s38, s25
	v_lshl_add_u64 v[140:141], s[36:37], 0, v[130:131]
	s_mov_b32 m0, s38
	s_nop 0
	global_load_lds_dwordx4 v[140:141], off
	v_lshl_add_u64 v[140:141], s[36:37], 0, v[128:129]
	s_add_i32 m0, s38, 0x2000
	s_nop 0
	global_load_lds_dwordx4 v[140:141], off
	s_waitcnt vmcnt(6)
	s_barrier
	s_setprio 1
	v_mfma_f32_16x16x32_bf16 v[52:55], v[200:203], v[164:167], v[52:55]
	v_mfma_f32_16x16x32_bf16 v[48:51], v[208:211], v[164:167], v[48:51]
	v_mfma_f32_16x16x32_bf16 v[36:39], v[200:203], v[172:175], v[36:39]
	v_mfma_f32_16x16x32_bf16 v[32:35], v[208:211], v[172:175], v[32:35]
	v_mfma_f32_16x16x32_bf16 v[20:23], v[200:203], v[180:183], v[20:23]
	v_mfma_f32_16x16x32_bf16 v[16:19], v[208:211], v[180:183], v[16:19]
	v_mfma_f32_16x16x32_bf16 v[4:7], v[200:203], v[188:191], v[4:7]
	v_mfma_f32_16x16x32_bf16 v[0:3], v[208:211], v[188:191], v[0:3]
	v_mfma_f32_16x16x32_bf16 v[52:55], v[204:207], v[168:171], v[52:55]
	v_mfma_f32_16x16x32_bf16 v[48:51], v[212:215], v[168:171], v[48:51]
	v_mfma_f32_16x16x32_bf16 v[36:39], v[204:207], v[176:179], v[36:39]
	v_mfma_f32_16x16x32_bf16 v[32:35], v[212:215], v[176:179], v[32:35]
	v_mfma_f32_16x16x32_bf16 v[20:23], v[204:207], v[184:187], v[20:23]
	v_mfma_f32_16x16x32_bf16 v[16:19], v[212:215], v[184:187], v[16:19]
	v_mfma_f32_16x16x32_bf16 v[4:7], v[204:207], v[192:195], v[4:7]
	v_mfma_f32_16x16x32_bf16 v[0:3], v[212:215], v[192:195], v[0:3]
	s_setprio 0
	s_add_i32 s59, s59, 2
	s_add_u32 s22, s22, 0x100
	s_addc_u32 s23, s23, 0
	s_add_u32 s57, s57, 0x100
	s_addc_u32 s58, s58, 0
	s_cmp_gt_u32 s59, 13
	s_barrier
	s_cbranch_scc0 .LBB0_878
	v_lshl_add_u32 v190, s20, 8, v146
	v_lshl_or_b32 v191, s33, 8, v148
	v_lshl_add_u32 v184, v190, 10, v191
	v_and_b32_e32 v190, 16, v198
	v_lshrrev_b32_e32 v191, 1, v190
	v_add_u32_e32 v190, v190, v191
	v_lshl_add_u32 v176, v184, 1, v190
	v_add_u32_e32 v177, 0x8000, v176
	v_add_u32_e32 v178, 0x10000, v176
	v_add_u32_e32 v179, 0x18000, v176
	v_add_u32_e32 v180, 0x40000, v176
	v_add_u32_e32 v181, 0x48000, v176
	v_add_u32_e32 v182, 0x50000, v176
	v_add_u32_e32 v183, 0x58000, v176
	v_mov_b32_e32 v186, 0xbfb8aa3b
	v_mov_b32_e32 v187, 0xbfb8aa3b
	v_mov_b32_e32 v188, 1.0
	v_mov_b32_e32 v189, 1.0
	s_and_b64 vcc, exec, s[6:7]
	global_load_dwordx4 v[200:203], v176, s[88:89]
	global_load_dwordx4 v[204:207], v176, s[4:5]
	global_load_dwordx4 v[208:211], v176, s[88:89] offset:256
	global_load_dwordx4 v[212:215], v176, s[4:5] offset:256
	global_load_dwordx4 v[216:219], v177, s[88:89]
	global_load_dwordx4 v[220:223], v177, s[4:5]
	global_load_dwordx4 v[224:227], v177, s[88:89] offset:256
	global_load_dwordx4 v[228:231], v177, s[4:5] offset:256
	global_load_dwordx4 v[232:235], v178, s[88:89]
	global_load_dwordx4 v[236:239], v178, s[4:5]
	global_load_dwordx4 v[240:243], v178, s[88:89] offset:256
	global_load_dwordx4 v[244:247], v178, s[4:5] offset:256
	global_load_dwordx4 v[152:155], v179, s[88:89]
	global_load_dwordx4 v[156:159], v179, s[4:5]
	global_load_dwordx4 v[160:163], v179, s[88:89] offset:256
	global_load_dwordx4 v[164:167], v179, s[4:5] offset:256
	v_pk_mul_f32 v[124:125], v[124:125], v[186:187]
	v_pk_mul_f32 v[126:127], v[126:127], v[186:187]
	v_pk_mul_f32 v[120:121], v[120:121], v[186:187]
	v_pk_mul_f32 v[122:123], v[122:123], v[186:187]
	v_exp_f32_e32 v124, v124
	v_exp_f32_e32 v125, v125
	v_exp_f32_e32 v126, v126
	v_exp_f32_e32 v127, v127
	v_exp_f32_e32 v120, v120
	v_exp_f32_e32 v121, v121
	v_exp_f32_e32 v122, v122
	v_exp_f32_e32 v123, v123
	v_pk_add_f32 v[124:125], v[124:125], v[188:189]
	v_pk_add_f32 v[126:127], v[126:127], v[188:189]
	v_pk_add_f32 v[120:121], v[120:121], v[188:189]
	v_pk_add_f32 v[122:123], v[122:123], v[188:189]
	v_rcp_f32_e32 v124, v124
	v_rcp_f32_e32 v125, v125
	v_rcp_f32_e32 v126, v126
	v_rcp_f32_e32 v127, v127
	v_rcp_f32_e32 v120, v120
	v_rcp_f32_e32 v121, v121
	v_rcp_f32_e32 v122, v122
	v_rcp_f32_e32 v123, v123
	v_pk_mul_f32 v[116:117], v[116:117], v[186:187]
	v_pk_mul_f32 v[118:119], v[118:119], v[186:187]
	v_pk_mul_f32 v[112:113], v[112:113], v[186:187]
	v_pk_mul_f32 v[114:115], v[114:115], v[186:187]
	v_exp_f32_e32 v116, v116
	v_exp_f32_e32 v117, v117
	v_exp_f32_e32 v118, v118
	v_exp_f32_e32 v119, v119
	v_exp_f32_e32 v112, v112
	v_exp_f32_e32 v113, v113
	v_exp_f32_e32 v114, v114
	v_exp_f32_e32 v115, v115
	v_pk_add_f32 v[116:117], v[116:117], v[188:189]
	v_pk_add_f32 v[118:119], v[118:119], v[188:189]
	v_pk_add_f32 v[112:113], v[112:113], v[188:189]
	v_pk_add_f32 v[114:115], v[114:115], v[188:189]
	v_rcp_f32_e32 v116, v116
	v_rcp_f32_e32 v117, v117
	v_rcp_f32_e32 v118, v118
	v_rcp_f32_e32 v119, v119
	v_rcp_f32_e32 v112, v112
	v_rcp_f32_e32 v113, v113
	v_rcp_f32_e32 v114, v114
	v_rcp_f32_e32 v115, v115
	v_pk_mul_f32 v[108:109], v[108:109], v[186:187]
	v_pk_mul_f32 v[110:111], v[110:111], v[186:187]
	v_pk_mul_f32 v[104:105], v[104:105], v[186:187]
	v_pk_mul_f32 v[106:107], v[106:107], v[186:187]
	v_exp_f32_e32 v108, v108
	v_exp_f32_e32 v109, v109
	v_exp_f32_e32 v110, v110
	v_exp_f32_e32 v111, v111
	v_exp_f32_e32 v104, v104
	v_exp_f32_e32 v105, v105
	v_exp_f32_e32 v106, v106
	v_exp_f32_e32 v107, v107
	v_pk_add_f32 v[108:109], v[108:109], v[188:189]
	v_pk_add_f32 v[110:111], v[110:111], v[188:189]
	v_pk_add_f32 v[104:105], v[104:105], v[188:189]
	v_pk_add_f32 v[106:107], v[106:107], v[188:189]
	v_rcp_f32_e32 v108, v108
	v_rcp_f32_e32 v109, v109
	v_rcp_f32_e32 v110, v110
	v_rcp_f32_e32 v111, v111
	v_rcp_f32_e32 v104, v104
	v_rcp_f32_e32 v105, v105
	v_rcp_f32_e32 v106, v106
	v_rcp_f32_e32 v107, v107
	v_pk_mul_f32 v[100:101], v[100:101], v[186:187]
	v_pk_mul_f32 v[102:103], v[102:103], v[186:187]
	v_pk_mul_f32 v[96:97], v[96:97], v[186:187]
	v_pk_mul_f32 v[98:99], v[98:99], v[186:187]
	v_exp_f32_e32 v100, v100
	v_exp_f32_e32 v101, v101
	v_exp_f32_e32 v102, v102
	v_exp_f32_e32 v103, v103
	v_exp_f32_e32 v96, v96
	v_exp_f32_e32 v97, v97
	v_exp_f32_e32 v98, v98
	v_exp_f32_e32 v99, v99
	v_pk_add_f32 v[100:101], v[100:101], v[188:189]
	v_pk_add_f32 v[102:103], v[102:103], v[188:189]
	v_pk_add_f32 v[96:97], v[96:97], v[188:189]
	v_pk_add_f32 v[98:99], v[98:99], v[188:189]
	v_rcp_f32_e32 v100, v100
	v_rcp_f32_e32 v101, v101
	v_rcp_f32_e32 v102, v102
	v_rcp_f32_e32 v103, v103
	v_rcp_f32_e32 v96, v96
	v_rcp_f32_e32 v97, v97
	v_rcp_f32_e32 v98, v98
	v_rcp_f32_e32 v99, v99
	v_pk_mul_f32 v[92:93], v[92:93], v[186:187]
	v_pk_mul_f32 v[94:95], v[94:95], v[186:187]
	v_pk_mul_f32 v[88:89], v[88:89], v[186:187]
	v_pk_mul_f32 v[90:91], v[90:91], v[186:187]
	v_exp_f32_e32 v92, v92
	v_exp_f32_e32 v93, v93
	v_exp_f32_e32 v94, v94
	v_exp_f32_e32 v95, v95
	v_exp_f32_e32 v88, v88
	v_exp_f32_e32 v89, v89
	v_exp_f32_e32 v90, v90
	v_exp_f32_e32 v91, v91
	v_pk_add_f32 v[92:93], v[92:93], v[188:189]
	v_pk_add_f32 v[94:95], v[94:95], v[188:189]
	v_pk_add_f32 v[88:89], v[88:89], v[188:189]
	v_pk_add_f32 v[90:91], v[90:91], v[188:189]
	v_rcp_f32_e32 v92, v92
	v_rcp_f32_e32 v93, v93
	v_rcp_f32_e32 v94, v94
	v_rcp_f32_e32 v95, v95
	v_rcp_f32_e32 v88, v88
	v_rcp_f32_e32 v89, v89
	v_rcp_f32_e32 v90, v90
	v_rcp_f32_e32 v91, v91
	v_pk_mul_f32 v[84:85], v[84:85], v[186:187]
	v_pk_mul_f32 v[86:87], v[86:87], v[186:187]
	v_pk_mul_f32 v[80:81], v[80:81], v[186:187]
	v_pk_mul_f32 v[82:83], v[82:83], v[186:187]
	v_exp_f32_e32 v84, v84
	v_exp_f32_e32 v85, v85
	v_exp_f32_e32 v86, v86
	v_exp_f32_e32 v87, v87
	v_exp_f32_e32 v80, v80
	v_exp_f32_e32 v81, v81
	v_exp_f32_e32 v82, v82
	v_exp_f32_e32 v83, v83
	v_pk_add_f32 v[84:85], v[84:85], v[188:189]
	v_pk_add_f32 v[86:87], v[86:87], v[188:189]
	v_pk_add_f32 v[80:81], v[80:81], v[188:189]
	v_pk_add_f32 v[82:83], v[82:83], v[188:189]
	v_rcp_f32_e32 v84, v84
	v_rcp_f32_e32 v85, v85
	v_rcp_f32_e32 v86, v86
	v_rcp_f32_e32 v87, v87
	v_rcp_f32_e32 v80, v80
	v_rcp_f32_e32 v81, v81
	v_rcp_f32_e32 v82, v82
	v_rcp_f32_e32 v83, v83
	v_pk_mul_f32 v[76:77], v[76:77], v[186:187]
	v_pk_mul_f32 v[78:79], v[78:79], v[186:187]
	v_pk_mul_f32 v[72:73], v[72:73], v[186:187]
	v_pk_mul_f32 v[74:75], v[74:75], v[186:187]
	v_exp_f32_e32 v76, v76
	v_exp_f32_e32 v77, v77
	v_exp_f32_e32 v78, v78
	v_exp_f32_e32 v79, v79
	v_exp_f32_e32 v72, v72
	v_exp_f32_e32 v73, v73
	v_exp_f32_e32 v74, v74
	v_exp_f32_e32 v75, v75
	v_pk_add_f32 v[76:77], v[76:77], v[188:189]
	v_pk_add_f32 v[78:79], v[78:79], v[188:189]
	v_pk_add_f32 v[72:73], v[72:73], v[188:189]
	v_pk_add_f32 v[74:75], v[74:75], v[188:189]
	v_rcp_f32_e32 v76, v76
	v_rcp_f32_e32 v77, v77
	v_rcp_f32_e32 v78, v78
	v_rcp_f32_e32 v79, v79
	v_rcp_f32_e32 v72, v72
	v_rcp_f32_e32 v73, v73
	v_rcp_f32_e32 v74, v74
	v_rcp_f32_e32 v75, v75
	v_pk_mul_f32 v[68:69], v[68:69], v[186:187]
	v_pk_mul_f32 v[70:71], v[70:71], v[186:187]
	v_pk_mul_f32 v[64:65], v[64:65], v[186:187]
	v_pk_mul_f32 v[66:67], v[66:67], v[186:187]
	v_exp_f32_e32 v68, v68
	v_exp_f32_e32 v69, v69
	v_exp_f32_e32 v70, v70
	v_exp_f32_e32 v71, v71
	v_exp_f32_e32 v64, v64
	v_exp_f32_e32 v65, v65
	v_exp_f32_e32 v66, v66
	v_exp_f32_e32 v67, v67
	v_pk_add_f32 v[68:69], v[68:69], v[188:189]
	v_pk_add_f32 v[70:71], v[70:71], v[188:189]
	v_pk_add_f32 v[64:65], v[64:65], v[188:189]
	v_pk_add_f32 v[66:67], v[66:67], v[188:189]
	v_rcp_f32_e32 v68, v68
	v_rcp_f32_e32 v69, v69
	v_rcp_f32_e32 v70, v70
	v_rcp_f32_e32 v71, v71
	v_rcp_f32_e32 v64, v64
	v_rcp_f32_e32 v65, v65
	v_rcp_f32_e32 v66, v66
	v_rcp_f32_e32 v67, v67
	v_pk_mul_f32 v[60:61], v[60:61], v[186:187]
	v_pk_mul_f32 v[62:63], v[62:63], v[186:187]
	v_pk_mul_f32 v[56:57], v[56:57], v[186:187]
	v_pk_mul_f32 v[58:59], v[58:59], v[186:187]
	v_exp_f32_e32 v60, v60
	v_exp_f32_e32 v61, v61
	v_exp_f32_e32 v62, v62
	v_exp_f32_e32 v63, v63
	v_exp_f32_e32 v56, v56
	v_exp_f32_e32 v57, v57
	v_exp_f32_e32 v58, v58
	v_exp_f32_e32 v59, v59
	v_pk_add_f32 v[60:61], v[60:61], v[188:189]
	v_pk_add_f32 v[62:63], v[62:63], v[188:189]
	v_pk_add_f32 v[56:57], v[56:57], v[188:189]
	v_pk_add_f32 v[58:59], v[58:59], v[188:189]
	v_rcp_f32_e32 v60, v60
	v_rcp_f32_e32 v61, v61
	v_rcp_f32_e32 v62, v62
	v_rcp_f32_e32 v63, v63
	v_rcp_f32_e32 v56, v56
	v_rcp_f32_e32 v57, v57
	v_rcp_f32_e32 v58, v58
	v_rcp_f32_e32 v59, v59
	s_waitcnt vmcnt(14)
	v_permlane16_swap_b32_e32 v200, v202
	v_permlane16_swap_b32_e32 v201, v203
	v_permlane16_swap_b32_e32 v204, v206
	v_permlane16_swap_b32_e32 v205, v207
	v_lshlrev_b32_e32 v168, 16, v200
	v_and_b32_e32 v169, 0xffff0000, v200
	v_lshlrev_b32_e32 v200, 16, v201
	v_and_b32_e32 v201, 0xffff0000, v201
	v_lshlrev_b32_e32 v170, 16, v202
	v_and_b32_e32 v171, 0xffff0000, v202
	v_lshlrev_b32_e32 v202, 16, v203
	v_and_b32_e32 v203, 0xffff0000, v203
	v_lshlrev_b32_e32 v172, 16, v204
	v_and_b32_e32 v173, 0xffff0000, v204
	v_lshlrev_b32_e32 v204, 16, v205
	v_and_b32_e32 v205, 0xffff0000, v205
	v_lshlrev_b32_e32 v174, 16, v206
	v_and_b32_e32 v175, 0xffff0000, v206
	v_lshlrev_b32_e32 v206, 16, v207
	v_and_b32_e32 v207, 0xffff0000, v207
	v_pk_fma_f32 v[124:125], v[124:125], v[172:173], v[168:169]
	v_pk_fma_f32 v[126:127], v[126:127], v[204:205], v[200:201]
	v_pk_fma_f32 v[120:121], v[120:121], v[174:175], v[170:171]
	v_pk_fma_f32 v[122:123], v[122:123], v[206:207], v[202:203]
	v_cvt_pk_bf16_f32 v168, v124, v125
	v_cvt_pk_bf16_f32 v169, v126, v127
	v_cvt_pk_bf16_f32 v170, v120, v121
	v_cvt_pk_bf16_f32 v171, v122, v123
	s_nop 1
	v_permlane16_swap_b32_e32 v168, v170
	v_permlane16_swap_b32_e32 v169, v171
	global_store_dwordx4 v176, v[168:171], s[0:1]
	global_load_dwordx4 v[200:203], v180, s[88:89]
	global_load_dwordx4 v[204:207], v180, s[4:5]
	v_pk_mul_f32 v[52:53], v[52:53], v[186:187]
	v_pk_mul_f32 v[54:55], v[54:55], v[186:187]
	v_pk_mul_f32 v[48:49], v[48:49], v[186:187]
	v_pk_mul_f32 v[50:51], v[50:51], v[186:187]
	v_exp_f32_e32 v52, v52
	v_exp_f32_e32 v53, v53
	v_exp_f32_e32 v54, v54
	v_exp_f32_e32 v55, v55
	v_exp_f32_e32 v48, v48
	v_exp_f32_e32 v49, v49
	v_exp_f32_e32 v50, v50
	v_exp_f32_e32 v51, v51
	v_pk_add_f32 v[52:53], v[52:53], v[188:189]
	v_pk_add_f32 v[54:55], v[54:55], v[188:189]
	v_pk_add_f32 v[48:49], v[48:49], v[188:189]
	v_pk_add_f32 v[50:51], v[50:51], v[188:189]
	v_rcp_f32_e32 v52, v52
	v_rcp_f32_e32 v53, v53
	v_rcp_f32_e32 v54, v54
	v_rcp_f32_e32 v55, v55
	v_rcp_f32_e32 v48, v48
	v_rcp_f32_e32 v49, v49
	v_rcp_f32_e32 v50, v50
	v_rcp_f32_e32 v51, v51
	s_waitcnt vmcnt(15)
	v_permlane16_swap_b32_e32 v208, v210
	v_permlane16_swap_b32_e32 v209, v211
	v_permlane16_swap_b32_e32 v212, v214
	v_permlane16_swap_b32_e32 v213, v215
	v_lshlrev_b32_e32 v168, 16, v208
	v_and_b32_e32 v169, 0xffff0000, v208
	v_lshlrev_b32_e32 v208, 16, v209
	v_and_b32_e32 v209, 0xffff0000, v209
	v_lshlrev_b32_e32 v170, 16, v210
	v_and_b32_e32 v171, 0xffff0000, v210
	v_lshlrev_b32_e32 v210, 16, v211
	v_and_b32_e32 v211, 0xffff0000, v211
	v_lshlrev_b32_e32 v172, 16, v212
	v_and_b32_e32 v173, 0xffff0000, v212
	v_lshlrev_b32_e32 v212, 16, v213
	v_and_b32_e32 v213, 0xffff0000, v213
	v_lshlrev_b32_e32 v174, 16, v214
	v_and_b32_e32 v175, 0xffff0000, v214
	v_lshlrev_b32_e32 v214, 16, v215
	v_and_b32_e32 v215, 0xffff0000, v215
	v_pk_fma_f32 v[116:117], v[116:117], v[172:173], v[168:169]
	v_pk_fma_f32 v[118:119], v[118:119], v[212:213], v[208:209]
	v_pk_fma_f32 v[112:113], v[112:113], v[174:175], v[170:171]
	v_pk_fma_f32 v[114:115], v[114:115], v[214:215], v[210:211]
	v_cvt_pk_bf16_f32 v168, v116, v117
	v_cvt_pk_bf16_f32 v169, v118, v119
	v_cvt_pk_bf16_f32 v170, v112, v113
	v_cvt_pk_bf16_f32 v171, v114, v115
	s_nop 1
	v_permlane16_swap_b32_e32 v168, v170
	v_permlane16_swap_b32_e32 v169, v171
	global_store_dwordx4 v176, v[168:171], s[0:1] offset:256
	global_load_dwordx4 v[208:211], v180, s[88:89] offset:256
	global_load_dwordx4 v[212:215], v180, s[4:5] offset:256
	v_pk_mul_f32 v[44:45], v[44:45], v[186:187]
	v_pk_mul_f32 v[46:47], v[46:47], v[186:187]
	v_pk_mul_f32 v[40:41], v[40:41], v[186:187]
	v_pk_mul_f32 v[42:43], v[42:43], v[186:187]
	v_exp_f32_e32 v44, v44
	v_exp_f32_e32 v45, v45
	v_exp_f32_e32 v46, v46
	v_exp_f32_e32 v47, v47
	v_exp_f32_e32 v40, v40
	v_exp_f32_e32 v41, v41
	v_exp_f32_e32 v42, v42
	v_exp_f32_e32 v43, v43
	v_pk_add_f32 v[44:45], v[44:45], v[188:189]
	v_pk_add_f32 v[46:47], v[46:47], v[188:189]
	v_pk_add_f32 v[40:41], v[40:41], v[188:189]
	v_pk_add_f32 v[42:43], v[42:43], v[188:189]
	v_rcp_f32_e32 v44, v44
	v_rcp_f32_e32 v45, v45
	v_rcp_f32_e32 v46, v46
	v_rcp_f32_e32 v47, v47
	v_rcp_f32_e32 v40, v40
	v_rcp_f32_e32 v41, v41
	v_rcp_f32_e32 v42, v42
	v_rcp_f32_e32 v43, v43
	s_waitcnt vmcnt(16)
	v_permlane16_swap_b32_e32 v216, v218
	v_permlane16_swap_b32_e32 v217, v219
	v_permlane16_swap_b32_e32 v220, v222
	v_permlane16_swap_b32_e32 v221, v223
	v_lshlrev_b32_e32 v168, 16, v216
	v_and_b32_e32 v169, 0xffff0000, v216
	v_lshlrev_b32_e32 v216, 16, v217
	v_and_b32_e32 v217, 0xffff0000, v217
	v_lshlrev_b32_e32 v170, 16, v218
	v_and_b32_e32 v171, 0xffff0000, v218
	v_lshlrev_b32_e32 v218, 16, v219
	v_and_b32_e32 v219, 0xffff0000, v219
	v_lshlrev_b32_e32 v172, 16, v220
	v_and_b32_e32 v173, 0xffff0000, v220
	v_lshlrev_b32_e32 v220, 16, v221
	v_and_b32_e32 v221, 0xffff0000, v221
	v_lshlrev_b32_e32 v174, 16, v222
	v_and_b32_e32 v175, 0xffff0000, v222
	v_lshlrev_b32_e32 v222, 16, v223
	v_and_b32_e32 v223, 0xffff0000, v223
	v_pk_fma_f32 v[108:109], v[108:109], v[172:173], v[168:169]
	v_pk_fma_f32 v[110:111], v[110:111], v[220:221], v[216:217]
	v_pk_fma_f32 v[104:105], v[104:105], v[174:175], v[170:171]
	v_pk_fma_f32 v[106:107], v[106:107], v[222:223], v[218:219]
	v_cvt_pk_bf16_f32 v168, v108, v109
	v_cvt_pk_bf16_f32 v169, v110, v111
	v_cvt_pk_bf16_f32 v170, v104, v105
	v_cvt_pk_bf16_f32 v171, v106, v107
	s_nop 1
	v_permlane16_swap_b32_e32 v168, v170
	v_permlane16_swap_b32_e32 v169, v171
	global_store_dwordx4 v177, v[168:171], s[0:1]
	global_load_dwordx4 v[216:219], v181, s[88:89]
	global_load_dwordx4 v[220:223], v181, s[4:5]
	v_pk_mul_f32 v[36:37], v[36:37], v[186:187]
	v_pk_mul_f32 v[38:39], v[38:39], v[186:187]
	v_pk_mul_f32 v[32:33], v[32:33], v[186:187]
	v_pk_mul_f32 v[34:35], v[34:35], v[186:187]
	v_exp_f32_e32 v36, v36
	v_exp_f32_e32 v37, v37
	v_exp_f32_e32 v38, v38
	v_exp_f32_e32 v39, v39
	v_exp_f32_e32 v32, v32
	v_exp_f32_e32 v33, v33
	v_exp_f32_e32 v34, v34
	v_exp_f32_e32 v35, v35
	v_pk_add_f32 v[36:37], v[36:37], v[188:189]
	v_pk_add_f32 v[38:39], v[38:39], v[188:189]
	v_pk_add_f32 v[32:33], v[32:33], v[188:189]
	v_pk_add_f32 v[34:35], v[34:35], v[188:189]
	v_rcp_f32_e32 v36, v36
	v_rcp_f32_e32 v37, v37
	v_rcp_f32_e32 v38, v38
	v_rcp_f32_e32 v39, v39
	v_rcp_f32_e32 v32, v32
	v_rcp_f32_e32 v33, v33
	v_rcp_f32_e32 v34, v34
	v_rcp_f32_e32 v35, v35
	s_waitcnt vmcnt(17)
	v_permlane16_swap_b32_e32 v224, v226
	v_permlane16_swap_b32_e32 v225, v227
	v_permlane16_swap_b32_e32 v228, v230
	v_permlane16_swap_b32_e32 v229, v231
	v_lshlrev_b32_e32 v168, 16, v224
	v_and_b32_e32 v169, 0xffff0000, v224
	v_lshlrev_b32_e32 v224, 16, v225
	v_and_b32_e32 v225, 0xffff0000, v225
	v_lshlrev_b32_e32 v170, 16, v226
	v_and_b32_e32 v171, 0xffff0000, v226
	v_lshlrev_b32_e32 v226, 16, v227
	v_and_b32_e32 v227, 0xffff0000, v227
	v_lshlrev_b32_e32 v172, 16, v228
	v_and_b32_e32 v173, 0xffff0000, v228
	v_lshlrev_b32_e32 v228, 16, v229
	v_and_b32_e32 v229, 0xffff0000, v229
	v_lshlrev_b32_e32 v174, 16, v230
	v_and_b32_e32 v175, 0xffff0000, v230
	v_lshlrev_b32_e32 v230, 16, v231
	v_and_b32_e32 v231, 0xffff0000, v231
	v_pk_fma_f32 v[100:101], v[100:101], v[172:173], v[168:169]
	v_pk_fma_f32 v[102:103], v[102:103], v[228:229], v[224:225]
	v_pk_fma_f32 v[96:97], v[96:97], v[174:175], v[170:171]
	v_pk_fma_f32 v[98:99], v[98:99], v[230:231], v[226:227]
	v_cvt_pk_bf16_f32 v168, v100, v101
	v_cvt_pk_bf16_f32 v169, v102, v103
	v_cvt_pk_bf16_f32 v170, v96, v97
	v_cvt_pk_bf16_f32 v171, v98, v99
	s_nop 1
	v_permlane16_swap_b32_e32 v168, v170
	v_permlane16_swap_b32_e32 v169, v171
	global_store_dwordx4 v177, v[168:171], s[0:1] offset:256
	global_load_dwordx4 v[224:227], v181, s[88:89] offset:256
	global_load_dwordx4 v[228:231], v181, s[4:5] offset:256
	v_pk_mul_f32 v[28:29], v[28:29], v[186:187]
	v_pk_mul_f32 v[30:31], v[30:31], v[186:187]
	v_pk_mul_f32 v[24:25], v[24:25], v[186:187]
	v_pk_mul_f32 v[26:27], v[26:27], v[186:187]
	v_exp_f32_e32 v28, v28
	v_exp_f32_e32 v29, v29
	v_exp_f32_e32 v30, v30
	v_exp_f32_e32 v31, v31
	v_exp_f32_e32 v24, v24
	v_exp_f32_e32 v25, v25
	v_exp_f32_e32 v26, v26
	v_exp_f32_e32 v27, v27
	v_pk_add_f32 v[28:29], v[28:29], v[188:189]
	v_pk_add_f32 v[30:31], v[30:31], v[188:189]
	v_pk_add_f32 v[24:25], v[24:25], v[188:189]
	v_pk_add_f32 v[26:27], v[26:27], v[188:189]
	v_rcp_f32_e32 v28, v28
	v_rcp_f32_e32 v29, v29
	v_rcp_f32_e32 v30, v30
	v_rcp_f32_e32 v31, v31
	v_rcp_f32_e32 v24, v24
	v_rcp_f32_e32 v25, v25
	v_rcp_f32_e32 v26, v26
	v_rcp_f32_e32 v27, v27
	s_waitcnt vmcnt(18)
	v_permlane16_swap_b32_e32 v232, v234
	v_permlane16_swap_b32_e32 v233, v235
	v_permlane16_swap_b32_e32 v236, v238
	v_permlane16_swap_b32_e32 v237, v239
	v_lshlrev_b32_e32 v168, 16, v232
	v_and_b32_e32 v169, 0xffff0000, v232
	v_lshlrev_b32_e32 v232, 16, v233
	v_and_b32_e32 v233, 0xffff0000, v233
	v_lshlrev_b32_e32 v170, 16, v234
	v_and_b32_e32 v171, 0xffff0000, v234
	v_lshlrev_b32_e32 v234, 16, v235
	v_and_b32_e32 v235, 0xffff0000, v235
	v_lshlrev_b32_e32 v172, 16, v236
	v_and_b32_e32 v173, 0xffff0000, v236
	v_lshlrev_b32_e32 v236, 16, v237
	v_and_b32_e32 v237, 0xffff0000, v237
	v_lshlrev_b32_e32 v174, 16, v238
	v_and_b32_e32 v175, 0xffff0000, v238
	v_lshlrev_b32_e32 v238, 16, v239
	v_and_b32_e32 v239, 0xffff0000, v239
	v_pk_fma_f32 v[92:93], v[92:93], v[172:173], v[168:169]
	v_pk_fma_f32 v[94:95], v[94:95], v[236:237], v[232:233]
	v_pk_fma_f32 v[88:89], v[88:89], v[174:175], v[170:171]
	v_pk_fma_f32 v[90:91], v[90:91], v[238:239], v[234:235]
	v_cvt_pk_bf16_f32 v168, v92, v93
	v_cvt_pk_bf16_f32 v169, v94, v95
	v_cvt_pk_bf16_f32 v170, v88, v89
	v_cvt_pk_bf16_f32 v171, v90, v91
	s_nop 1
	v_permlane16_swap_b32_e32 v168, v170
	v_permlane16_swap_b32_e32 v169, v171
	global_store_dwordx4 v178, v[168:171], s[0:1]
	global_load_dwordx4 v[232:235], v182, s[88:89]
	global_load_dwordx4 v[236:239], v182, s[4:5]
	v_pk_mul_f32 v[20:21], v[20:21], v[186:187]
	v_pk_mul_f32 v[22:23], v[22:23], v[186:187]
	v_pk_mul_f32 v[16:17], v[16:17], v[186:187]
	v_pk_mul_f32 v[18:19], v[18:19], v[186:187]
	v_exp_f32_e32 v20, v20
	v_exp_f32_e32 v21, v21
	v_exp_f32_e32 v22, v22
	v_exp_f32_e32 v23, v23
	v_exp_f32_e32 v16, v16
	v_exp_f32_e32 v17, v17
	v_exp_f32_e32 v18, v18
	v_exp_f32_e32 v19, v19
	v_pk_add_f32 v[20:21], v[20:21], v[188:189]
	v_pk_add_f32 v[22:23], v[22:23], v[188:189]
	v_pk_add_f32 v[16:17], v[16:17], v[188:189]
	v_pk_add_f32 v[18:19], v[18:19], v[188:189]
	v_rcp_f32_e32 v20, v20
	v_rcp_f32_e32 v21, v21
	v_rcp_f32_e32 v22, v22
	v_rcp_f32_e32 v23, v23
	v_rcp_f32_e32 v16, v16
	v_rcp_f32_e32 v17, v17
	v_rcp_f32_e32 v18, v18
	v_rcp_f32_e32 v19, v19
	s_waitcnt vmcnt(19)
	v_permlane16_swap_b32_e32 v240, v242
	v_permlane16_swap_b32_e32 v241, v243
	v_permlane16_swap_b32_e32 v244, v246
	v_permlane16_swap_b32_e32 v245, v247
	v_lshlrev_b32_e32 v168, 16, v240
	v_and_b32_e32 v169, 0xffff0000, v240
	v_lshlrev_b32_e32 v240, 16, v241
	v_and_b32_e32 v241, 0xffff0000, v241
	v_lshlrev_b32_e32 v170, 16, v242
	v_and_b32_e32 v171, 0xffff0000, v242
	v_lshlrev_b32_e32 v242, 16, v243
	v_and_b32_e32 v243, 0xffff0000, v243
	v_lshlrev_b32_e32 v172, 16, v244
	v_and_b32_e32 v173, 0xffff0000, v244
	v_lshlrev_b32_e32 v244, 16, v245
	v_and_b32_e32 v245, 0xffff0000, v245
	v_lshlrev_b32_e32 v174, 16, v246
	v_and_b32_e32 v175, 0xffff0000, v246
	v_lshlrev_b32_e32 v246, 16, v247
	v_and_b32_e32 v247, 0xffff0000, v247
	v_pk_fma_f32 v[84:85], v[84:85], v[172:173], v[168:169]
	v_pk_fma_f32 v[86:87], v[86:87], v[244:245], v[240:241]
	v_pk_fma_f32 v[80:81], v[80:81], v[174:175], v[170:171]
	v_pk_fma_f32 v[82:83], v[82:83], v[246:247], v[242:243]
	v_cvt_pk_bf16_f32 v168, v84, v85
	v_cvt_pk_bf16_f32 v169, v86, v87
	v_cvt_pk_bf16_f32 v170, v80, v81
	v_cvt_pk_bf16_f32 v171, v82, v83
	s_nop 1
	v_permlane16_swap_b32_e32 v168, v170
	v_permlane16_swap_b32_e32 v169, v171
	global_store_dwordx4 v178, v[168:171], s[0:1] offset:256
	global_load_dwordx4 v[240:243], v182, s[88:89] offset:256
	global_load_dwordx4 v[244:247], v182, s[4:5] offset:256
	v_pk_mul_f32 v[12:13], v[12:13], v[186:187]
	v_pk_mul_f32 v[14:15], v[14:15], v[186:187]
	v_pk_mul_f32 v[8:9], v[8:9], v[186:187]
	v_pk_mul_f32 v[10:11], v[10:11], v[186:187]
	v_exp_f32_e32 v12, v12
	v_exp_f32_e32 v13, v13
	v_exp_f32_e32 v14, v14
	v_exp_f32_e32 v15, v15
	v_exp_f32_e32 v8, v8
	v_exp_f32_e32 v9, v9
	v_exp_f32_e32 v10, v10
	v_exp_f32_e32 v11, v11
	v_pk_add_f32 v[12:13], v[12:13], v[188:189]
	v_pk_add_f32 v[14:15], v[14:15], v[188:189]
	v_pk_add_f32 v[8:9], v[8:9], v[188:189]
	v_pk_add_f32 v[10:11], v[10:11], v[188:189]
	v_rcp_f32_e32 v12, v12
	v_rcp_f32_e32 v13, v13
	v_rcp_f32_e32 v14, v14
	v_rcp_f32_e32 v15, v15
	v_rcp_f32_e32 v8, v8
	v_rcp_f32_e32 v9, v9
	v_rcp_f32_e32 v10, v10
	v_rcp_f32_e32 v11, v11
	s_waitcnt vmcnt(20)
	v_permlane16_swap_b32_e32 v152, v154
	v_permlane16_swap_b32_e32 v153, v155
	v_permlane16_swap_b32_e32 v156, v158
	v_permlane16_swap_b32_e32 v157, v159
	v_lshlrev_b32_e32 v168, 16, v152
	v_and_b32_e32 v169, 0xffff0000, v152
	v_lshlrev_b32_e32 v152, 16, v153
	v_and_b32_e32 v153, 0xffff0000, v153
	v_lshlrev_b32_e32 v170, 16, v154
	v_and_b32_e32 v171, 0xffff0000, v154
	v_lshlrev_b32_e32 v154, 16, v155
	v_and_b32_e32 v155, 0xffff0000, v155
	v_lshlrev_b32_e32 v172, 16, v156
	v_and_b32_e32 v173, 0xffff0000, v156
	v_lshlrev_b32_e32 v156, 16, v157
	v_and_b32_e32 v157, 0xffff0000, v157
	v_lshlrev_b32_e32 v174, 16, v158
	v_and_b32_e32 v175, 0xffff0000, v158
	v_lshlrev_b32_e32 v158, 16, v159
	v_and_b32_e32 v159, 0xffff0000, v159
	v_pk_fma_f32 v[76:77], v[76:77], v[172:173], v[168:169]
	v_pk_fma_f32 v[78:79], v[78:79], v[156:157], v[152:153]
	v_pk_fma_f32 v[72:73], v[72:73], v[174:175], v[170:171]
	v_pk_fma_f32 v[74:75], v[74:75], v[158:159], v[154:155]
	v_cvt_pk_bf16_f32 v168, v76, v77
	v_cvt_pk_bf16_f32 v169, v78, v79
	v_cvt_pk_bf16_f32 v170, v72, v73
	v_cvt_pk_bf16_f32 v171, v74, v75
	s_nop 1
	v_permlane16_swap_b32_e32 v168, v170
	v_permlane16_swap_b32_e32 v169, v171
	global_store_dwordx4 v179, v[168:171], s[0:1]
	global_load_dwordx4 v[152:155], v183, s[88:89]
	global_load_dwordx4 v[156:159], v183, s[4:5]
	v_pk_mul_f32 v[4:5], v[4:5], v[186:187]
	v_pk_mul_f32 v[6:7], v[6:7], v[186:187]
	v_pk_mul_f32 v[0:1], v[0:1], v[186:187]
	v_pk_mul_f32 v[2:3], v[2:3], v[186:187]
	v_exp_f32_e32 v4, v4
	v_exp_f32_e32 v5, v5
	v_exp_f32_e32 v6, v6
	v_exp_f32_e32 v7, v7
	v_exp_f32_e32 v0, v0
	v_exp_f32_e32 v1, v1
	v_exp_f32_e32 v2, v2
	v_exp_f32_e32 v3, v3
	v_pk_add_f32 v[4:5], v[4:5], v[188:189]
	v_pk_add_f32 v[6:7], v[6:7], v[188:189]
	v_pk_add_f32 v[0:1], v[0:1], v[188:189]
	v_pk_add_f32 v[2:3], v[2:3], v[188:189]
	v_rcp_f32_e32 v4, v4
	v_rcp_f32_e32 v5, v5
	v_rcp_f32_e32 v6, v6
	v_rcp_f32_e32 v7, v7
	v_rcp_f32_e32 v0, v0
	v_rcp_f32_e32 v1, v1
	v_rcp_f32_e32 v2, v2
	v_rcp_f32_e32 v3, v3
	s_waitcnt vmcnt(21)
	v_permlane16_swap_b32_e32 v160, v162
	v_permlane16_swap_b32_e32 v161, v163
	v_permlane16_swap_b32_e32 v164, v166
	v_permlane16_swap_b32_e32 v165, v167
	v_lshlrev_b32_e32 v168, 16, v160
	v_and_b32_e32 v169, 0xffff0000, v160
	v_lshlrev_b32_e32 v160, 16, v161
	v_and_b32_e32 v161, 0xffff0000, v161
	v_lshlrev_b32_e32 v170, 16, v162
	v_and_b32_e32 v171, 0xffff0000, v162
	v_lshlrev_b32_e32 v162, 16, v163
	v_and_b32_e32 v163, 0xffff0000, v163
	v_lshlrev_b32_e32 v172, 16, v164
	v_and_b32_e32 v173, 0xffff0000, v164
	v_lshlrev_b32_e32 v164, 16, v165
	v_and_b32_e32 v165, 0xffff0000, v165
	v_lshlrev_b32_e32 v174, 16, v166
	v_and_b32_e32 v175, 0xffff0000, v166
	v_lshlrev_b32_e32 v166, 16, v167
	v_and_b32_e32 v167, 0xffff0000, v167
	v_pk_fma_f32 v[68:69], v[68:69], v[172:173], v[168:169]
	v_pk_fma_f32 v[70:71], v[70:71], v[164:165], v[160:161]
	v_pk_fma_f32 v[64:65], v[64:65], v[174:175], v[170:171]
	v_pk_fma_f32 v[66:67], v[66:67], v[166:167], v[162:163]
	v_cvt_pk_bf16_f32 v168, v68, v69
	v_cvt_pk_bf16_f32 v169, v70, v71
	v_cvt_pk_bf16_f32 v170, v64, v65
	v_cvt_pk_bf16_f32 v171, v66, v67
	s_nop 1
	v_permlane16_swap_b32_e32 v168, v170
	v_permlane16_swap_b32_e32 v169, v171
	global_store_dwordx4 v179, v[168:171], s[0:1] offset:256
	global_load_dwordx4 v[160:163], v183, s[88:89] offset:256
	global_load_dwordx4 v[164:167], v183, s[4:5] offset:256
	s_mov_b32 s33, s10
	s_mov_b32 s20, s14
	s_mov_b64 s[36:37], s[18:19]
	s_mov_b64 s[22:23], s[16:17]
	s_waitcnt vmcnt(21)
	v_permlane16_swap_b32_e32 v200, v202
	v_permlane16_swap_b32_e32 v201, v203
	v_permlane16_swap_b32_e32 v204, v206
	v_permlane16_swap_b32_e32 v205, v207
	v_lshlrev_b32_e32 v168, 16, v200
	v_and_b32_e32 v169, 0xffff0000, v200
	v_lshlrev_b32_e32 v200, 16, v201
	v_and_b32_e32 v201, 0xffff0000, v201
	v_lshlrev_b32_e32 v170, 16, v202
	v_and_b32_e32 v171, 0xffff0000, v202
	v_lshlrev_b32_e32 v202, 16, v203
	v_and_b32_e32 v203, 0xffff0000, v203
	v_lshlrev_b32_e32 v172, 16, v204
	v_and_b32_e32 v173, 0xffff0000, v204
	v_lshlrev_b32_e32 v204, 16, v205
	v_and_b32_e32 v205, 0xffff0000, v205
	v_lshlrev_b32_e32 v174, 16, v206
	v_and_b32_e32 v175, 0xffff0000, v206
	v_lshlrev_b32_e32 v206, 16, v207
	v_and_b32_e32 v207, 0xffff0000, v207
	v_pk_fma_f32 v[60:61], v[60:61], v[172:173], v[168:169]
	v_pk_fma_f32 v[62:63], v[62:63], v[204:205], v[200:201]
	v_pk_fma_f32 v[56:57], v[56:57], v[174:175], v[170:171]
	v_pk_fma_f32 v[58:59], v[58:59], v[206:207], v[202:203]
	v_cvt_pk_bf16_f32 v168, v60, v61
	v_cvt_pk_bf16_f32 v169, v62, v63
	v_cvt_pk_bf16_f32 v170, v56, v57
	v_cvt_pk_bf16_f32 v171, v58, v59
	s_nop 1
	v_permlane16_swap_b32_e32 v168, v170
	v_permlane16_swap_b32_e32 v169, v171
	global_store_dwordx4 v180, v[168:171], s[0:1]
	s_waitcnt vmcnt(19)
	v_permlane16_swap_b32_e32 v208, v210
	v_permlane16_swap_b32_e32 v209, v211
	v_permlane16_swap_b32_e32 v212, v214
	v_permlane16_swap_b32_e32 v213, v215
	v_lshlrev_b32_e32 v168, 16, v208
	v_and_b32_e32 v169, 0xffff0000, v208
	v_lshlrev_b32_e32 v208, 16, v209
	v_and_b32_e32 v209, 0xffff0000, v209
	v_lshlrev_b32_e32 v170, 16, v210
	v_and_b32_e32 v171, 0xffff0000, v210
	v_lshlrev_b32_e32 v210, 16, v211
	v_and_b32_e32 v211, 0xffff0000, v211
	v_lshlrev_b32_e32 v172, 16, v212
	v_and_b32_e32 v173, 0xffff0000, v212
	v_lshlrev_b32_e32 v212, 16, v213
	v_and_b32_e32 v213, 0xffff0000, v213
	v_lshlrev_b32_e32 v174, 16, v214
	v_and_b32_e32 v175, 0xffff0000, v214
	v_lshlrev_b32_e32 v214, 16, v215
	v_and_b32_e32 v215, 0xffff0000, v215
	v_pk_fma_f32 v[52:53], v[52:53], v[172:173], v[168:169]
	v_pk_fma_f32 v[54:55], v[54:55], v[212:213], v[208:209]
	v_pk_fma_f32 v[48:49], v[48:49], v[174:175], v[170:171]
	v_pk_fma_f32 v[50:51], v[50:51], v[214:215], v[210:211]
	v_cvt_pk_bf16_f32 v168, v52, v53
	v_cvt_pk_bf16_f32 v169, v54, v55
	v_cvt_pk_bf16_f32 v170, v48, v49
	v_cvt_pk_bf16_f32 v171, v50, v51
	s_nop 1
	v_permlane16_swap_b32_e32 v168, v170
	v_permlane16_swap_b32_e32 v169, v171
	global_store_dwordx4 v180, v[168:171], s[0:1] offset:256
	s_waitcnt vmcnt(17)
	v_permlane16_swap_b32_e32 v216, v218
	v_permlane16_swap_b32_e32 v217, v219
	v_permlane16_swap_b32_e32 v220, v222
	v_permlane16_swap_b32_e32 v221, v223
	v_lshlrev_b32_e32 v168, 16, v216
	v_and_b32_e32 v169, 0xffff0000, v216
	v_lshlrev_b32_e32 v216, 16, v217
	v_and_b32_e32 v217, 0xffff0000, v217
	v_lshlrev_b32_e32 v170, 16, v218
	v_and_b32_e32 v171, 0xffff0000, v218
	v_lshlrev_b32_e32 v218, 16, v219
	v_and_b32_e32 v219, 0xffff0000, v219
	v_lshlrev_b32_e32 v172, 16, v220
	v_and_b32_e32 v173, 0xffff0000, v220
	v_lshlrev_b32_e32 v220, 16, v221
	v_and_b32_e32 v221, 0xffff0000, v221
	v_lshlrev_b32_e32 v174, 16, v222
	v_and_b32_e32 v175, 0xffff0000, v222
	v_lshlrev_b32_e32 v222, 16, v223
	v_and_b32_e32 v223, 0xffff0000, v223
	v_pk_fma_f32 v[44:45], v[44:45], v[172:173], v[168:169]
	v_pk_fma_f32 v[46:47], v[46:47], v[220:221], v[216:217]
	v_pk_fma_f32 v[40:41], v[40:41], v[174:175], v[170:171]
	v_pk_fma_f32 v[42:43], v[42:43], v[222:223], v[218:219]
	v_cvt_pk_bf16_f32 v168, v44, v45
	v_cvt_pk_bf16_f32 v169, v46, v47
	v_cvt_pk_bf16_f32 v170, v40, v41
	v_cvt_pk_bf16_f32 v171, v42, v43
	s_nop 1
	v_permlane16_swap_b32_e32 v168, v170
	v_permlane16_swap_b32_e32 v169, v171
	global_store_dwordx4 v181, v[168:171], s[0:1]
	s_waitcnt vmcnt(15)
	v_permlane16_swap_b32_e32 v224, v226
	v_permlane16_swap_b32_e32 v225, v227
	v_permlane16_swap_b32_e32 v228, v230
	v_permlane16_swap_b32_e32 v229, v231
	v_lshlrev_b32_e32 v168, 16, v224
	v_and_b32_e32 v169, 0xffff0000, v224
	v_lshlrev_b32_e32 v224, 16, v225
	v_and_b32_e32 v225, 0xffff0000, v225
	v_lshlrev_b32_e32 v170, 16, v226
	v_and_b32_e32 v171, 0xffff0000, v226
	v_lshlrev_b32_e32 v226, 16, v227
	v_and_b32_e32 v227, 0xffff0000, v227
	v_lshlrev_b32_e32 v172, 16, v228
	v_and_b32_e32 v173, 0xffff0000, v228
	v_lshlrev_b32_e32 v228, 16, v229
	v_and_b32_e32 v229, 0xffff0000, v229
	v_lshlrev_b32_e32 v174, 16, v230
	v_and_b32_e32 v175, 0xffff0000, v230
	v_lshlrev_b32_e32 v230, 16, v231
	v_and_b32_e32 v231, 0xffff0000, v231
	v_pk_fma_f32 v[36:37], v[36:37], v[172:173], v[168:169]
	v_pk_fma_f32 v[38:39], v[38:39], v[228:229], v[224:225]
	v_pk_fma_f32 v[32:33], v[32:33], v[174:175], v[170:171]
	v_pk_fma_f32 v[34:35], v[34:35], v[230:231], v[226:227]
	v_cvt_pk_bf16_f32 v168, v36, v37
	v_cvt_pk_bf16_f32 v169, v38, v39
	v_cvt_pk_bf16_f32 v170, v32, v33
	v_cvt_pk_bf16_f32 v171, v34, v35
	s_nop 1
	v_permlane16_swap_b32_e32 v168, v170
	v_permlane16_swap_b32_e32 v169, v171
	global_store_dwordx4 v181, v[168:171], s[0:1] offset:256
	s_waitcnt vmcnt(13)
	v_permlane16_swap_b32_e32 v232, v234
	v_permlane16_swap_b32_e32 v233, v235
	v_permlane16_swap_b32_e32 v236, v238
	v_permlane16_swap_b32_e32 v237, v239
	v_lshlrev_b32_e32 v168, 16, v232
	v_and_b32_e32 v169, 0xffff0000, v232
	v_lshlrev_b32_e32 v232, 16, v233
	v_and_b32_e32 v233, 0xffff0000, v233
	v_lshlrev_b32_e32 v170, 16, v234
	v_and_b32_e32 v171, 0xffff0000, v234
	v_lshlrev_b32_e32 v234, 16, v235
	v_and_b32_e32 v235, 0xffff0000, v235
	v_lshlrev_b32_e32 v172, 16, v236
	v_and_b32_e32 v173, 0xffff0000, v236
	v_lshlrev_b32_e32 v236, 16, v237
	v_and_b32_e32 v237, 0xffff0000, v237
	v_lshlrev_b32_e32 v174, 16, v238
	v_and_b32_e32 v175, 0xffff0000, v238
	v_lshlrev_b32_e32 v238, 16, v239
	v_and_b32_e32 v239, 0xffff0000, v239
	v_pk_fma_f32 v[28:29], v[28:29], v[172:173], v[168:169]
	v_pk_fma_f32 v[30:31], v[30:31], v[236:237], v[232:233]
	v_pk_fma_f32 v[24:25], v[24:25], v[174:175], v[170:171]
	v_pk_fma_f32 v[26:27], v[26:27], v[238:239], v[234:235]
	v_cvt_pk_bf16_f32 v168, v28, v29
	v_cvt_pk_bf16_f32 v169, v30, v31
	v_cvt_pk_bf16_f32 v170, v24, v25
	v_cvt_pk_bf16_f32 v171, v26, v27
	s_nop 1
	v_permlane16_swap_b32_e32 v168, v170
	v_permlane16_swap_b32_e32 v169, v171
	global_store_dwordx4 v182, v[168:171], s[0:1]
	s_waitcnt vmcnt(11)
	v_permlane16_swap_b32_e32 v240, v242
	v_permlane16_swap_b32_e32 v241, v243
	v_permlane16_swap_b32_e32 v244, v246
	v_permlane16_swap_b32_e32 v245, v247
	v_lshlrev_b32_e32 v168, 16, v240
	v_and_b32_e32 v169, 0xffff0000, v240
	v_lshlrev_b32_e32 v240, 16, v241
	v_and_b32_e32 v241, 0xffff0000, v241
	v_lshlrev_b32_e32 v170, 16, v242
	v_and_b32_e32 v171, 0xffff0000, v242
	v_lshlrev_b32_e32 v242, 16, v243
	v_and_b32_e32 v243, 0xffff0000, v243
	v_lshlrev_b32_e32 v172, 16, v244
	v_and_b32_e32 v173, 0xffff0000, v244
	v_lshlrev_b32_e32 v244, 16, v245
	v_and_b32_e32 v245, 0xffff0000, v245
	v_lshlrev_b32_e32 v174, 16, v246
	v_and_b32_e32 v175, 0xffff0000, v246
	v_lshlrev_b32_e32 v246, 16, v247
	v_and_b32_e32 v247, 0xffff0000, v247
	v_pk_fma_f32 v[20:21], v[20:21], v[172:173], v[168:169]
	v_pk_fma_f32 v[22:23], v[22:23], v[244:245], v[240:241]
	v_pk_fma_f32 v[16:17], v[16:17], v[174:175], v[170:171]
	v_pk_fma_f32 v[18:19], v[18:19], v[246:247], v[242:243]
	v_cvt_pk_bf16_f32 v168, v20, v21
	v_cvt_pk_bf16_f32 v169, v22, v23
	v_cvt_pk_bf16_f32 v170, v16, v17
	v_cvt_pk_bf16_f32 v171, v18, v19
	s_nop 1
	v_permlane16_swap_b32_e32 v168, v170
	v_permlane16_swap_b32_e32 v169, v171
	global_store_dwordx4 v182, v[168:171], s[0:1] offset:256
	s_waitcnt vmcnt(9)
	v_permlane16_swap_b32_e32 v152, v154
	v_permlane16_swap_b32_e32 v153, v155
	v_permlane16_swap_b32_e32 v156, v158
	v_permlane16_swap_b32_e32 v157, v159
	v_lshlrev_b32_e32 v168, 16, v152
	v_and_b32_e32 v169, 0xffff0000, v152
	v_lshlrev_b32_e32 v152, 16, v153
	v_and_b32_e32 v153, 0xffff0000, v153
	v_lshlrev_b32_e32 v170, 16, v154
	v_and_b32_e32 v171, 0xffff0000, v154
	v_lshlrev_b32_e32 v154, 16, v155
	v_and_b32_e32 v155, 0xffff0000, v155
	v_lshlrev_b32_e32 v172, 16, v156
	v_and_b32_e32 v173, 0xffff0000, v156
	v_lshlrev_b32_e32 v156, 16, v157
	v_and_b32_e32 v157, 0xffff0000, v157
	v_lshlrev_b32_e32 v174, 16, v158
	v_and_b32_e32 v175, 0xffff0000, v158
	v_lshlrev_b32_e32 v158, 16, v159
	v_and_b32_e32 v159, 0xffff0000, v159
	v_pk_fma_f32 v[12:13], v[12:13], v[172:173], v[168:169]
	v_pk_fma_f32 v[14:15], v[14:15], v[156:157], v[152:153]
	v_pk_fma_f32 v[8:9], v[8:9], v[174:175], v[170:171]
	v_pk_fma_f32 v[10:11], v[10:11], v[158:159], v[154:155]
	v_cvt_pk_bf16_f32 v168, v12, v13
	v_cvt_pk_bf16_f32 v169, v14, v15
	v_cvt_pk_bf16_f32 v170, v8, v9
	v_cvt_pk_bf16_f32 v171, v10, v11
	s_nop 1
	v_permlane16_swap_b32_e32 v168, v170
	v_permlane16_swap_b32_e32 v169, v171
	global_store_dwordx4 v183, v[168:171], s[0:1]
	s_waitcnt vmcnt(7)
	v_permlane16_swap_b32_e32 v160, v162
	v_permlane16_swap_b32_e32 v161, v163
	v_permlane16_swap_b32_e32 v164, v166
	v_permlane16_swap_b32_e32 v165, v167
	v_lshlrev_b32_e32 v168, 16, v160
	v_and_b32_e32 v169, 0xffff0000, v160
	v_lshlrev_b32_e32 v160, 16, v161
	v_and_b32_e32 v161, 0xffff0000, v161
	v_lshlrev_b32_e32 v170, 16, v162
	v_and_b32_e32 v171, 0xffff0000, v162
	v_lshlrev_b32_e32 v162, 16, v163
	v_and_b32_e32 v163, 0xffff0000, v163
	v_lshlrev_b32_e32 v172, 16, v164
	v_and_b32_e32 v173, 0xffff0000, v164
	v_lshlrev_b32_e32 v164, 16, v165
	v_and_b32_e32 v165, 0xffff0000, v165
	v_lshlrev_b32_e32 v174, 16, v166
	v_and_b32_e32 v175, 0xffff0000, v166
	v_lshlrev_b32_e32 v166, 16, v167
	v_and_b32_e32 v167, 0xffff0000, v167
	v_pk_fma_f32 v[4:5], v[4:5], v[172:173], v[168:169]
	v_pk_fma_f32 v[6:7], v[6:7], v[164:165], v[160:161]
	v_pk_fma_f32 v[0:1], v[0:1], v[174:175], v[170:171]
	v_pk_fma_f32 v[2:3], v[2:3], v[166:167], v[162:163]
	v_cvt_pk_bf16_f32 v168, v4, v5
	v_cvt_pk_bf16_f32 v169, v6, v7
	v_cvt_pk_bf16_f32 v170, v0, v1
	v_cvt_pk_bf16_f32 v171, v2, v3
	s_nop 1
	v_permlane16_swap_b32_e32 v168, v170
	v_permlane16_swap_b32_e32 v169, v171
	global_store_dwordx4 v183, v[168:171], s[0:1] offset:256
	s_cbranch_vccz .LBB0_871
	s_waitcnt vmcnt(0)
	s_cmpk_gt_u32 s24, 0xff
	s_cbranch_scc1 .LBB0_882
	s_barrier

.LBB0_1614:
	ds_read_b128 v[140:143], v149
	ds_read_b128 v[152:155], v149 offset:1024
	ds_read_b128 v[156:159], v149 offset:2048
	ds_read_b128 v[160:163], v149 offset:3072
	s_add_u32 s28, s26, 0xfffc0080
	s_addc_u32 s29, s27, -1
	s_cmp_eq_u32 s48, 12
	s_cselect_b32 s31, s17, s29
	s_cselect_b32 s30, s19, s28
	s_cselect_b32 s29, s44, s47
	s_cselect_b32 s28, s45, s46
	v_lshl_add_u64 v[144:145], s[26:27], 0, v[132:133]
	s_add_i32 m0, s25, 0xc000
	ds_read_b128 v[164:167], v150
	ds_read_b128 v[168:171], v150 offset:1024
	ds_read_b128 v[172:175], v150 offset:2048
	ds_read_b128 v[176:179], v150 offset:3072
	ds_read_b128 v[180:183], v150 offset:4096
	ds_read_b128 v[184:187], v150 offset:5120
	ds_read_b128 v[188:191], v150 offset:6144
	ds_read_b128 v[192:195], v150 offset:7168
	global_load_lds_dwordx4 v[144:145], off
	v_lshl_add_u64 v[144:145], s[26:27], 0, v[134:135]
	s_add_i32 m0, s25, 0xe000
	s_nop 0
	global_load_lds_dwordx4 v[144:145], off
	s_waitcnt lgkmcnt(8)
	s_barrier
	s_waitcnt lgkmcnt(0)
	s_setprio 1
	s_waitcnt lgkmcnt(0)
	v_mfma_f32_16x16x32_bf16 v[124:127], v[140:143], v[164:167], v[124:127]
	v_mfma_f32_16x16x32_bf16 v[120:123], v[156:159], v[164:167], v[120:123]
	v_mfma_f32_16x16x32_bf16 v[108:111], v[140:143], v[172:175], v[108:111]
	v_mfma_f32_16x16x32_bf16 v[104:107], v[156:159], v[172:175], v[104:107]
	v_mfma_f32_16x16x32_bf16 v[92:95], v[140:143], v[180:183], v[92:95]
	v_mfma_f32_16x16x32_bf16 v[88:91], v[156:159], v[180:183], v[88:91]
	v_mfma_f32_16x16x32_bf16 v[76:79], v[140:143], v[188:191], v[76:79]
	v_mfma_f32_16x16x32_bf16 v[72:75], v[156:159], v[188:191], v[72:75]
	v_mfma_f32_16x16x32_bf16 v[124:127], v[152:155], v[168:171], v[124:127]
	v_mfma_f32_16x16x32_bf16 v[120:123], v[160:163], v[168:171], v[120:123]
	v_mfma_f32_16x16x32_bf16 v[108:111], v[152:155], v[176:179], v[108:111]
	v_mfma_f32_16x16x32_bf16 v[104:107], v[160:163], v[176:179], v[104:107]
	v_mfma_f32_16x16x32_bf16 v[92:95], v[152:155], v[184:187], v[92:95]
	v_mfma_f32_16x16x32_bf16 v[88:91], v[160:163], v[184:187], v[88:91]
	v_mfma_f32_16x16x32_bf16 v[76:79], v[152:155], v[192:195], v[76:79]
	v_mfma_f32_16x16x32_bf16 v[72:75], v[160:163], v[192:195], v[72:75]
	s_setprio 0
	s_barrier
	s_add_i32 s49, s42, s35
	v_lshl_add_u64 v[144:145], s[28:29], 0, v[130:131]
	s_mov_b32 m0, s49
	ds_read_b128 v[200:203], v151
	ds_read_b128 v[204:207], v151 offset:1024
	ds_read_b128 v[208:211], v151 offset:2048
	ds_read_b128 v[212:215], v151 offset:3072
	global_load_lds_dwordx4 v[144:145], off
	v_lshl_add_u64 v[196:197], s[28:29], 0, v[128:129]
	s_add_i32 m0, s49, 0x2000
	s_nop 0
	global_load_lds_dwordx4 v[196:197], off
	s_barrier
	s_waitcnt lgkmcnt(0)
	s_setprio 1
	s_waitcnt lgkmcnt(0)
	v_mfma_f32_16x16x32_bf16 v[116:119], v[200:203], v[164:167], v[116:119]
	v_mfma_f32_16x16x32_bf16 v[112:115], v[208:211], v[164:167], v[112:115]
	v_mfma_f32_16x16x32_bf16 v[100:103], v[200:203], v[172:175], v[100:103]
	v_mfma_f32_16x16x32_bf16 v[96:99], v[208:211], v[172:175], v[96:99]
	v_mfma_f32_16x16x32_bf16 v[84:87], v[200:203], v[180:183], v[84:87]
	v_mfma_f32_16x16x32_bf16 v[80:83], v[208:211], v[180:183], v[80:83]
	v_mfma_f32_16x16x32_bf16 v[68:71], v[200:203], v[188:191], v[68:71]
	v_mfma_f32_16x16x32_bf16 v[64:67], v[208:211], v[188:191], v[64:67]
	v_mfma_f32_16x16x32_bf16 v[116:119], v[204:207], v[168:171], v[116:119]
	v_mfma_f32_16x16x32_bf16 v[112:115], v[212:215], v[168:171], v[112:115]
	v_mfma_f32_16x16x32_bf16 v[100:103], v[204:207], v[176:179], v[100:103]
	v_mfma_f32_16x16x32_bf16 v[96:99], v[212:215], v[176:179], v[96:99]
	v_mfma_f32_16x16x32_bf16 v[84:87], v[204:207], v[184:187], v[84:87]
	v_mfma_f32_16x16x32_bf16 v[80:83], v[212:215], v[184:187], v[80:83]
	v_mfma_f32_16x16x32_bf16 v[68:71], v[204:207], v[192:195], v[68:71]
	v_mfma_f32_16x16x32_bf16 v[64:67], v[212:215], v[192:195], v[64:67]
	s_setprio 0
	s_mov_b32 m0, s25
	v_lshl_add_u64 v[216:217], s[30:31], 0, v[130:131]
	s_barrier
	ds_read_b128 v[164:167], v150 offset:16384
	ds_read_b128 v[168:171], v150 offset:17408
	ds_read_b128 v[172:175], v150 offset:18432
	ds_read_b128 v[176:179], v150 offset:19456
	ds_read_b128 v[180:183], v150 offset:20480
	ds_read_b128 v[184:187], v150 offset:21504
	ds_read_b128 v[188:191], v150 offset:22528
	ds_read_b128 v[192:195], v150 offset:23552
	global_load_lds_dwordx4 v[216:217], off
	v_lshl_add_u64 v[218:219], s[30:31], 0, v[128:129]
	s_mov_b32 m0, s36
	s_nop 0
	global_load_lds_dwordx4 v[218:219], off
	s_barrier
	s_waitcnt lgkmcnt(0)
	s_setprio 1
	s_waitcnt lgkmcnt(0)
	v_mfma_f32_16x16x32_bf16 v[60:63], v[140:143], v[164:167], v[60:63]
	v_mfma_f32_16x16x32_bf16 v[56:59], v[156:159], v[164:167], v[56:59]
	v_mfma_f32_16x16x32_bf16 v[44:47], v[140:143], v[172:175], v[44:47]
	v_mfma_f32_16x16x32_bf16 v[40:43], v[156:159], v[172:175], v[40:43]
	v_mfma_f32_16x16x32_bf16 v[28:31], v[140:143], v[180:183], v[28:31]
	v_mfma_f32_16x16x32_bf16 v[24:27], v[156:159], v[180:183], v[24:27]
	v_mfma_f32_16x16x32_bf16 v[12:15], v[140:143], v[188:191], v[12:15]
	v_mfma_f32_16x16x32_bf16 v[8:11], v[156:159], v[188:191], v[8:11]
	v_mfma_f32_16x16x32_bf16 v[60:63], v[152:155], v[168:171], v[60:63]
	v_mfma_f32_16x16x32_bf16 v[56:59], v[160:163], v[168:171], v[56:59]
	v_mfma_f32_16x16x32_bf16 v[44:47], v[152:155], v[176:179], v[44:47]
	v_mfma_f32_16x16x32_bf16 v[40:43], v[160:163], v[176:179], v[40:43]
	v_mfma_f32_16x16x32_bf16 v[28:31], v[152:155], v[184:187], v[28:31]
	v_mfma_f32_16x16x32_bf16 v[24:27], v[160:163], v[184:187], v[24:27]
	v_mfma_f32_16x16x32_bf16 v[12:15], v[152:155], v[192:195], v[12:15]
	v_mfma_f32_16x16x32_bf16 v[8:11], v[160:163], v[192:195], v[8:11]
	s_setprio 0
	s_barrier
	s_add_u32 s50, s28, 0x40000
	s_addc_u32 s51, s29, 0
	s_add_i32 s49, s43, s35
	v_lshl_add_u64 v[140:141], s[50:51], 0, v[130:131]
	s_mov_b32 m0, s49
	s_nop 0
	global_load_lds_dwordx4 v[140:141], off
	v_lshl_add_u64 v[140:141], s[50:51], 0, v[128:129]
	s_add_i32 m0, s49, 0x2000
	s_nop 0
	global_load_lds_dwordx4 v[140:141], off
	s_waitcnt vmcnt(6)
	s_barrier
	s_setprio 1
	v_mfma_f32_16x16x32_bf16 v[52:55], v[200:203], v[164:167], v[52:55]
	v_mfma_f32_16x16x32_bf16 v[48:51], v[208:211], v[164:167], v[48:51]
	v_mfma_f32_16x16x32_bf16 v[36:39], v[200:203], v[172:175], v[36:39]
	v_mfma_f32_16x16x32_bf16 v[32:35], v[208:211], v[172:175], v[32:35]
	v_mfma_f32_16x16x32_bf16 v[20:23], v[200:203], v[180:183], v[20:23]
	v_mfma_f32_16x16x32_bf16 v[16:19], v[208:211], v[180:183], v[16:19]
	v_mfma_f32_16x16x32_bf16 v[4:7], v[200:203], v[188:191], v[4:7]
	v_mfma_f32_16x16x32_bf16 v[0:3], v[208:211], v[188:191], v[0:3]
	v_mfma_f32_16x16x32_bf16 v[52:55], v[204:207], v[168:171], v[52:55]
	v_mfma_f32_16x16x32_bf16 v[48:51], v[212:215], v[168:171], v[48:51]
	v_mfma_f32_16x16x32_bf16 v[36:39], v[204:207], v[176:179], v[36:39]
	v_mfma_f32_16x16x32_bf16 v[32:35], v[212:215], v[176:179], v[32:35]
	v_mfma_f32_16x16x32_bf16 v[20:23], v[204:207], v[184:187], v[20:23]
	v_mfma_f32_16x16x32_bf16 v[16:19], v[212:215], v[184:187], v[16:19]
	v_mfma_f32_16x16x32_bf16 v[4:7], v[204:207], v[192:195], v[4:7]
	v_mfma_f32_16x16x32_bf16 v[0:3], v[212:215], v[192:195], v[0:3]
	s_setprio 0
	s_add_i32 s49, 0, 0x18000
	v_add_u32_e32 v160, s49, v147
	s_barrier
	ds_read_b128 v[140:143], v160
	ds_read_b128 v[152:155], v160 offset:1024
	ds_read_b128 v[156:159], v160 offset:2048
	ds_read_b128 v[160:163], v160 offset:3072
	s_add_u32 s30, s30, 0x40000
	s_addc_u32 s31, s31, 0
	s_mov_b32 m0, s37
	v_lshl_add_u64 v[200:201], s[30:31], 0, v[130:131]
	ds_read_b128 v[164:167], v150 offset:32768
	ds_read_b128 v[168:171], v150 offset:33792
	ds_read_b128 v[172:175], v150 offset:34816
	ds_read_b128 v[176:179], v150 offset:35840
	ds_read_b128 v[180:183], v150 offset:36864
	ds_read_b128 v[184:187], v150 offset:37888
	ds_read_b128 v[188:191], v150 offset:38912
	ds_read_b128 v[192:195], v150 offset:39936
	global_load_lds_dwordx4 v[200:201], off
	v_lshl_add_u64 v[200:201], s[30:31], 0, v[128:129]
	s_mov_b32 m0, s38
	s_nop 0
	global_load_lds_dwordx4 v[200:201], off
	s_waitcnt lgkmcnt(8)
	s_barrier
	s_waitcnt lgkmcnt(0)
	s_setprio 1
	s_waitcnt lgkmcnt(0)
	v_mfma_f32_16x16x32_bf16 v[124:127], v[140:143], v[164:167], v[124:127]
	v_mfma_f32_16x16x32_bf16 v[120:123], v[156:159], v[164:167], v[120:123]
	v_mfma_f32_16x16x32_bf16 v[108:111], v[140:143], v[172:175], v[108:111]
	v_mfma_f32_16x16x32_bf16 v[104:107], v[156:159], v[172:175], v[104:107]
	v_mfma_f32_16x16x32_bf16 v[92:95], v[140:143], v[180:183], v[92:95]
	v_mfma_f32_16x16x32_bf16 v[88:91], v[156:159], v[180:183], v[88:91]
	v_mfma_f32_16x16x32_bf16 v[76:79], v[140:143], v[188:191], v[76:79]
	v_mfma_f32_16x16x32_bf16 v[72:75], v[156:159], v[188:191], v[72:75]
	v_mfma_f32_16x16x32_bf16 v[124:127], v[152:155], v[168:171], v[124:127]
	v_mfma_f32_16x16x32_bf16 v[120:123], v[160:163], v[168:171], v[120:123]
	v_mfma_f32_16x16x32_bf16 v[108:111], v[152:155], v[176:179], v[108:111]
	v_mfma_f32_16x16x32_bf16 v[104:107], v[160:163], v[176:179], v[104:107]
	v_mfma_f32_16x16x32_bf16 v[92:95], v[152:155], v[184:187], v[92:95]
	v_mfma_f32_16x16x32_bf16 v[88:91], v[160:163], v[184:187], v[88:91]
	v_mfma_f32_16x16x32_bf16 v[76:79], v[152:155], v[192:195], v[76:79]
	v_mfma_f32_16x16x32_bf16 v[72:75], v[160:163], v[192:195], v[72:75]
	s_setprio 0
	s_barrier
	s_add_i32 s30, 0, 0x1c000
	s_add_i32 s31, s49, s35
	v_add_u32_e32 v199, s30, v147
	v_lshl_add_u64 v[144:145], v[144:145], 0, s[6:7]
	s_mov_b32 m0, s31
	ds_read_b128 v[200:203], v199
	ds_read_b128 v[204:207], v199 offset:1024
	ds_read_b128 v[208:211], v199 offset:2048
	ds_read_b128 v[212:215], v199 offset:3072
	global_load_lds_dwordx4 v[144:145], off
	v_lshl_add_u64 v[144:145], v[196:197], 0, s[6:7]
	s_add_i32 m0, s31, 0x2000
	s_nop 0
	global_load_lds_dwordx4 v[144:145], off
	s_barrier
	s_waitcnt lgkmcnt(0)
	s_setprio 1
	s_waitcnt lgkmcnt(0)
	v_mfma_f32_16x16x32_bf16 v[116:119], v[200:203], v[164:167], v[116:119]
	v_mfma_f32_16x16x32_bf16 v[112:115], v[208:211], v[164:167], v[112:115]
	v_mfma_f32_16x16x32_bf16 v[100:103], v[200:203], v[172:175], v[100:103]
	v_mfma_f32_16x16x32_bf16 v[96:99], v[208:211], v[172:175], v[96:99]
	v_mfma_f32_16x16x32_bf16 v[84:87], v[200:203], v[180:183], v[84:87]
	v_mfma_f32_16x16x32_bf16 v[80:83], v[208:211], v[180:183], v[80:83]
	v_mfma_f32_16x16x32_bf16 v[68:71], v[200:203], v[188:191], v[68:71]
	v_mfma_f32_16x16x32_bf16 v[64:67], v[208:211], v[188:191], v[64:67]
	v_mfma_f32_16x16x32_bf16 v[116:119], v[204:207], v[168:171], v[116:119]
	v_mfma_f32_16x16x32_bf16 v[112:115], v[212:215], v[168:171], v[112:115]
	v_mfma_f32_16x16x32_bf16 v[100:103], v[204:207], v[176:179], v[100:103]
	v_mfma_f32_16x16x32_bf16 v[96:99], v[212:215], v[176:179], v[96:99]
	v_mfma_f32_16x16x32_bf16 v[84:87], v[204:207], v[184:187], v[84:87]
	v_mfma_f32_16x16x32_bf16 v[80:83], v[212:215], v[184:187], v[80:83]
	v_mfma_f32_16x16x32_bf16 v[68:71], v[204:207], v[192:195], v[68:71]
	v_mfma_f32_16x16x32_bf16 v[64:67], v[212:215], v[192:195], v[64:67]
	s_setprio 0
	s_mov_b32 m0, s40
	v_lshl_add_u64 v[144:145], v[216:217], 0, s[6:7]
	s_barrier
	ds_read_b128 v[164:167], v150 offset:49152
	ds_read_b128 v[168:171], v150 offset:50176
	ds_read_b128 v[172:175], v150 offset:51200
	ds_read_b128 v[176:179], v150 offset:52224
	ds_read_b128 v[180:183], v150 offset:53248
	ds_read_b128 v[184:187], v150 offset:54272
	ds_read_b128 v[188:191], v150 offset:55296
	ds_read_b128 v[192:195], v150 offset:56320
	global_load_lds_dwordx4 v[144:145], off
	v_lshl_add_u64 v[144:145], v[218:219], 0, s[6:7]
	s_mov_b32 m0, s41
	s_nop 0
	global_load_lds_dwordx4 v[144:145], off
	s_barrier
	s_waitcnt lgkmcnt(0)
	s_setprio 1
	s_waitcnt lgkmcnt(0)
	v_mfma_f32_16x16x32_bf16 v[60:63], v[140:143], v[164:167], v[60:63]
	v_mfma_f32_16x16x32_bf16 v[56:59], v[156:159], v[164:167], v[56:59]
	v_mfma_f32_16x16x32_bf16 v[44:47], v[140:143], v[172:175], v[44:47]
	v_mfma_f32_16x16x32_bf16 v[40:43], v[156:159], v[172:175], v[40:43]
	v_mfma_f32_16x16x32_bf16 v[28:31], v[140:143], v[180:183], v[28:31]
	v_mfma_f32_16x16x32_bf16 v[24:27], v[156:159], v[180:183], v[24:27]
	v_mfma_f32_16x16x32_bf16 v[12:15], v[140:143], v[188:191], v[12:15]
	v_mfma_f32_16x16x32_bf16 v[8:11], v[156:159], v[188:191], v[8:11]
	v_mfma_f32_16x16x32_bf16 v[60:63], v[152:155], v[168:171], v[60:63]
	v_mfma_f32_16x16x32_bf16 v[56:59], v[160:163], v[168:171], v[56:59]
	v_mfma_f32_16x16x32_bf16 v[44:47], v[152:155], v[176:179], v[44:47]
	v_mfma_f32_16x16x32_bf16 v[40:43], v[160:163], v[176:179], v[40:43]
	v_mfma_f32_16x16x32_bf16 v[28:31], v[152:155], v[184:187], v[28:31]
	v_mfma_f32_16x16x32_bf16 v[24:27], v[160:163], v[184:187], v[24:27]
	v_mfma_f32_16x16x32_bf16 v[12:15], v[152:155], v[192:195], v[12:15]
	v_mfma_f32_16x16x32_bf16 v[8:11], v[160:163], v[192:195], v[8:11]
	s_setprio 0
	s_barrier
	s_add_u32 s28, s28, 0x40080
	s_addc_u32 s29, s29, 0
	s_add_i32 s30, s30, s35
	v_lshl_add_u64 v[140:141], s[28:29], 0, v[130:131]
	s_mov_b32 m0, s30
	s_nop 0
	global_load_lds_dwordx4 v[140:141], off
	v_lshl_add_u64 v[140:141], s[28:29], 0, v[128:129]
	s_add_i32 m0, s30, 0x2000
	s_nop 0
	global_load_lds_dwordx4 v[140:141], off
	s_waitcnt vmcnt(6)
	s_barrier
	s_setprio 1
	v_mfma_f32_16x16x32_bf16 v[52:55], v[200:203], v[164:167], v[52:55]
	v_mfma_f32_16x16x32_bf16 v[48:51], v[208:211], v[164:167], v[48:51]
	v_mfma_f32_16x16x32_bf16 v[36:39], v[200:203], v[172:175], v[36:39]
	v_mfma_f32_16x16x32_bf16 v[32:35], v[208:211], v[172:175], v[32:35]
	v_mfma_f32_16x16x32_bf16 v[20:23], v[200:203], v[180:183], v[20:23]
	v_mfma_f32_16x16x32_bf16 v[16:19], v[208:211], v[180:183], v[16:19]
	v_mfma_f32_16x16x32_bf16 v[4:7], v[200:203], v[188:191], v[4:7]
	v_mfma_f32_16x16x32_bf16 v[0:3], v[208:211], v[188:191], v[0:3]
	v_mfma_f32_16x16x32_bf16 v[52:55], v[204:207], v[168:171], v[52:55]
	v_mfma_f32_16x16x32_bf16 v[48:51], v[212:215], v[168:171], v[48:51]
	v_mfma_f32_16x16x32_bf16 v[36:39], v[204:207], v[176:179], v[36:39]
	v_mfma_f32_16x16x32_bf16 v[32:35], v[212:215], v[176:179], v[32:35]
	v_mfma_f32_16x16x32_bf16 v[20:23], v[204:207], v[184:187], v[20:23]
	v_mfma_f32_16x16x32_bf16 v[16:19], v[212:215], v[184:187], v[16:19]
	v_mfma_f32_16x16x32_bf16 v[4:7], v[204:207], v[192:195], v[4:7]
	v_mfma_f32_16x16x32_bf16 v[0:3], v[212:215], v[192:195], v[0:3]
	s_setprio 0
	s_add_i32 s48, s48, 2
	s_add_u32 s26, s26, 0x100
	s_addc_u32 s27, s27, 0
	s_add_u32 s46, s46, 0x100
	s_addc_u32 s47, s47, 0
	s_cmp_gt_u32 s48, 13
	s_barrier
	s_cbranch_scc0 .LBB0_1614
	v_lshl_add_u32 v190, s24, 8, v146
	v_lshl_or_b32 v191, s33, 8, v148
	v_lshl_add_u32 v184, v190, 10, v191
	v_and_b32_e32 v190, 16, v198
	v_lshrrev_b32_e32 v191, 1, v190
	v_add_u32_e32 v190, v190, v191
	v_lshl_add_u32 v176, v184, 1, v190
	v_add_u32_e32 v177, 0x8000, v176
	v_add_u32_e32 v178, 0x10000, v176
	v_add_u32_e32 v179, 0x18000, v176
	v_add_u32_e32 v180, 0x40000, v176
	v_add_u32_e32 v181, 0x48000, v176
	v_add_u32_e32 v182, 0x50000, v176
	v_add_u32_e32 v183, 0x58000, v176
	v_and_b32_e32 v190, 8, v198
	v_sub_u32_e32 v191, v146, v190
	v_lshl_add_u32 v191, s24, 8, v191
	v_lshlrev_b32_e32 v184, 12, v191
	v_lshl_add_u32 v184, v190, 3, v184
	v_bfe_u32 v190, v198, 4, 2
	v_lshl_add_u32 v184, v190, 4, v184
	v_bfe_u32 v190, v198, 6, 2
	v_lshl_add_u32 v184, v190, 7, v184
	s_lshl_b32 s60, s33, 10
	v_add_u32_e32 v184, s60, v184
	v_mov_b32_e32 v186, 0xbfb8aa3b
	v_mov_b32_e32 v187, 0xbfb8aa3b
	v_mov_b32_e32 v188, 1.0
	v_mov_b32_e32 v189, 1.0
	s_and_b64 vcc, exec, s[0:1]
	global_load_dwordx4 v[200:203], v176, s[88:89]
	global_load_dwordx4 v[204:207], v176, s[4:5]
	global_load_dwordx4 v[208:211], v176, s[88:89] offset:256
	global_load_dwordx4 v[212:215], v176, s[4:5] offset:256
	global_load_dwordx4 v[216:219], v177, s[88:89]
	global_load_dwordx4 v[220:223], v177, s[4:5]
	global_load_dwordx4 v[224:227], v177, s[88:89] offset:256
	global_load_dwordx4 v[228:231], v177, s[4:5] offset:256
	global_load_dwordx4 v[232:235], v178, s[88:89]
	global_load_dwordx4 v[236:239], v178, s[4:5]
	global_load_dwordx4 v[240:243], v178, s[88:89] offset:256
	global_load_dwordx4 v[244:247], v178, s[4:5] offset:256
	global_load_dwordx4 v[152:155], v179, s[88:89]
	global_load_dwordx4 v[156:159], v179, s[4:5]
	global_load_dwordx4 v[160:163], v179, s[88:89] offset:256
	global_load_dwordx4 v[164:167], v179, s[4:5] offset:256
	v_pk_mul_f32 v[124:125], v[124:125], v[186:187]
	v_pk_mul_f32 v[126:127], v[126:127], v[186:187]
	v_pk_mul_f32 v[120:121], v[120:121], v[186:187]
	v_pk_mul_f32 v[122:123], v[122:123], v[186:187]
	v_exp_f32_e32 v124, v124
	v_exp_f32_e32 v125, v125
	v_exp_f32_e32 v126, v126
	v_exp_f32_e32 v127, v127
	v_exp_f32_e32 v120, v120
	v_exp_f32_e32 v121, v121
	v_exp_f32_e32 v122, v122
	v_exp_f32_e32 v123, v123
	v_pk_add_f32 v[124:125], v[124:125], v[188:189]
	v_pk_add_f32 v[126:127], v[126:127], v[188:189]
	v_pk_add_f32 v[120:121], v[120:121], v[188:189]
	v_pk_add_f32 v[122:123], v[122:123], v[188:189]
	v_rcp_f32_e32 v124, v124
	v_rcp_f32_e32 v125, v125
	v_rcp_f32_e32 v126, v126
	v_rcp_f32_e32 v127, v127
	v_rcp_f32_e32 v120, v120
	v_rcp_f32_e32 v121, v121
	v_rcp_f32_e32 v122, v122
	v_rcp_f32_e32 v123, v123
	v_pk_mul_f32 v[116:117], v[116:117], v[186:187]
	v_pk_mul_f32 v[118:119], v[118:119], v[186:187]
	v_pk_mul_f32 v[112:113], v[112:113], v[186:187]
	v_pk_mul_f32 v[114:115], v[114:115], v[186:187]
	v_exp_f32_e32 v116, v116
	v_exp_f32_e32 v117, v117
	v_exp_f32_e32 v118, v118
	v_exp_f32_e32 v119, v119
	v_exp_f32_e32 v112, v112
	v_exp_f32_e32 v113, v113
	v_exp_f32_e32 v114, v114
	v_exp_f32_e32 v115, v115
	v_pk_add_f32 v[116:117], v[116:117], v[188:189]
	v_pk_add_f32 v[118:119], v[118:119], v[188:189]
	v_pk_add_f32 v[112:113], v[112:113], v[188:189]
	v_pk_add_f32 v[114:115], v[114:115], v[188:189]
	v_rcp_f32_e32 v116, v116
	v_rcp_f32_e32 v117, v117
	v_rcp_f32_e32 v118, v118
	v_rcp_f32_e32 v119, v119
	v_rcp_f32_e32 v112, v112
	v_rcp_f32_e32 v113, v113
	v_rcp_f32_e32 v114, v114
	v_rcp_f32_e32 v115, v115
	v_pk_mul_f32 v[108:109], v[108:109], v[186:187]
	v_pk_mul_f32 v[110:111], v[110:111], v[186:187]
	v_pk_mul_f32 v[104:105], v[104:105], v[186:187]
	v_pk_mul_f32 v[106:107], v[106:107], v[186:187]
	v_exp_f32_e32 v108, v108
	v_exp_f32_e32 v109, v109
	v_exp_f32_e32 v110, v110
	v_exp_f32_e32 v111, v111
	v_exp_f32_e32 v104, v104
	v_exp_f32_e32 v105, v105
	v_exp_f32_e32 v106, v106
	v_exp_f32_e32 v107, v107
	v_pk_add_f32 v[108:109], v[108:109], v[188:189]
	v_pk_add_f32 v[110:111], v[110:111], v[188:189]
	v_pk_add_f32 v[104:105], v[104:105], v[188:189]
	v_pk_add_f32 v[106:107], v[106:107], v[188:189]
	v_rcp_f32_e32 v108, v108
	v_rcp_f32_e32 v109, v109
	v_rcp_f32_e32 v110, v110
	v_rcp_f32_e32 v111, v111
	v_rcp_f32_e32 v104, v104
	v_rcp_f32_e32 v105, v105
	v_rcp_f32_e32 v106, v106
	v_rcp_f32_e32 v107, v107
	v_pk_mul_f32 v[100:101], v[100:101], v[186:187]
	v_pk_mul_f32 v[102:103], v[102:103], v[186:187]
	v_pk_mul_f32 v[96:97], v[96:97], v[186:187]
	v_pk_mul_f32 v[98:99], v[98:99], v[186:187]
	v_exp_f32_e32 v100, v100
	v_exp_f32_e32 v101, v101
	v_exp_f32_e32 v102, v102
	v_exp_f32_e32 v103, v103
	v_exp_f32_e32 v96, v96
	v_exp_f32_e32 v97, v97
	v_exp_f32_e32 v98, v98
	v_exp_f32_e32 v99, v99
	v_pk_add_f32 v[100:101], v[100:101], v[188:189]
	v_pk_add_f32 v[102:103], v[102:103], v[188:189]
	v_pk_add_f32 v[96:97], v[96:97], v[188:189]
	v_pk_add_f32 v[98:99], v[98:99], v[188:189]
	v_rcp_f32_e32 v100, v100
	v_rcp_f32_e32 v101, v101
	v_rcp_f32_e32 v102, v102
	v_rcp_f32_e32 v103, v103
	v_rcp_f32_e32 v96, v96
	v_rcp_f32_e32 v97, v97
	v_rcp_f32_e32 v98, v98
	v_rcp_f32_e32 v99, v99
	v_pk_mul_f32 v[92:93], v[92:93], v[186:187]
	v_pk_mul_f32 v[94:95], v[94:95], v[186:187]
	v_pk_mul_f32 v[88:89], v[88:89], v[186:187]
	v_pk_mul_f32 v[90:91], v[90:91], v[186:187]
	v_exp_f32_e32 v92, v92
	v_exp_f32_e32 v93, v93
	v_exp_f32_e32 v94, v94
	v_exp_f32_e32 v95, v95
	v_exp_f32_e32 v88, v88
	v_exp_f32_e32 v89, v89
	v_exp_f32_e32 v90, v90
	v_exp_f32_e32 v91, v91
	v_pk_add_f32 v[92:93], v[92:93], v[188:189]
	v_pk_add_f32 v[94:95], v[94:95], v[188:189]
	v_pk_add_f32 v[88:89], v[88:89], v[188:189]
	v_pk_add_f32 v[90:91], v[90:91], v[188:189]
	v_rcp_f32_e32 v92, v92
	v_rcp_f32_e32 v93, v93
	v_rcp_f32_e32 v94, v94
	v_rcp_f32_e32 v95, v95
	v_rcp_f32_e32 v88, v88
	v_rcp_f32_e32 v89, v89
	v_rcp_f32_e32 v90, v90
	v_rcp_f32_e32 v91, v91
	v_pk_mul_f32 v[84:85], v[84:85], v[186:187]
	v_pk_mul_f32 v[86:87], v[86:87], v[186:187]
	v_pk_mul_f32 v[80:81], v[80:81], v[186:187]
	v_pk_mul_f32 v[82:83], v[82:83], v[186:187]
	v_exp_f32_e32 v84, v84
	v_exp_f32_e32 v85, v85
	v_exp_f32_e32 v86, v86
	v_exp_f32_e32 v87, v87
	v_exp_f32_e32 v80, v80
	v_exp_f32_e32 v81, v81
	v_exp_f32_e32 v82, v82
	v_exp_f32_e32 v83, v83
	v_pk_add_f32 v[84:85], v[84:85], v[188:189]
	v_pk_add_f32 v[86:87], v[86:87], v[188:189]
	v_pk_add_f32 v[80:81], v[80:81], v[188:189]
	v_pk_add_f32 v[82:83], v[82:83], v[188:189]
	v_rcp_f32_e32 v84, v84
	v_rcp_f32_e32 v85, v85
	v_rcp_f32_e32 v86, v86
	v_rcp_f32_e32 v87, v87
	v_rcp_f32_e32 v80, v80
	v_rcp_f32_e32 v81, v81
	v_rcp_f32_e32 v82, v82
	v_rcp_f32_e32 v83, v83
	v_pk_mul_f32 v[76:77], v[76:77], v[186:187]
	v_pk_mul_f32 v[78:79], v[78:79], v[186:187]
	v_pk_mul_f32 v[72:73], v[72:73], v[186:187]
	v_pk_mul_f32 v[74:75], v[74:75], v[186:187]
	v_exp_f32_e32 v76, v76
	v_exp_f32_e32 v77, v77
	v_exp_f32_e32 v78, v78
	v_exp_f32_e32 v79, v79
	v_exp_f32_e32 v72, v72
	v_exp_f32_e32 v73, v73
	v_exp_f32_e32 v74, v74
	v_exp_f32_e32 v75, v75
	v_pk_add_f32 v[76:77], v[76:77], v[188:189]
	v_pk_add_f32 v[78:79], v[78:79], v[188:189]
	v_pk_add_f32 v[72:73], v[72:73], v[188:189]
	v_pk_add_f32 v[74:75], v[74:75], v[188:189]
	v_rcp_f32_e32 v76, v76
	v_rcp_f32_e32 v77, v77
	v_rcp_f32_e32 v78, v78
	v_rcp_f32_e32 v79, v79
	v_rcp_f32_e32 v72, v72
	v_rcp_f32_e32 v73, v73
	v_rcp_f32_e32 v74, v74
	v_rcp_f32_e32 v75, v75
	v_pk_mul_f32 v[68:69], v[68:69], v[186:187]
	v_pk_mul_f32 v[70:71], v[70:71], v[186:187]
	v_pk_mul_f32 v[64:65], v[64:65], v[186:187]
	v_pk_mul_f32 v[66:67], v[66:67], v[186:187]
	v_exp_f32_e32 v68, v68
	v_exp_f32_e32 v69, v69
	v_exp_f32_e32 v70, v70
	v_exp_f32_e32 v71, v71
	v_exp_f32_e32 v64, v64
	v_exp_f32_e32 v65, v65
	v_exp_f32_e32 v66, v66
	v_exp_f32_e32 v67, v67
	v_pk_add_f32 v[68:69], v[68:69], v[188:189]
	v_pk_add_f32 v[70:71], v[70:71], v[188:189]
	v_pk_add_f32 v[64:65], v[64:65], v[188:189]
	v_pk_add_f32 v[66:67], v[66:67], v[188:189]
	v_rcp_f32_e32 v68, v68
	v_rcp_f32_e32 v69, v69
	v_rcp_f32_e32 v70, v70
	v_rcp_f32_e32 v71, v71
	v_rcp_f32_e32 v64, v64
	v_rcp_f32_e32 v65, v65
	v_rcp_f32_e32 v66, v66
	v_rcp_f32_e32 v67, v67
	v_pk_mul_f32 v[60:61], v[60:61], v[186:187]
	v_pk_mul_f32 v[62:63], v[62:63], v[186:187]
	v_pk_mul_f32 v[56:57], v[56:57], v[186:187]
	v_pk_mul_f32 v[58:59], v[58:59], v[186:187]
	v_exp_f32_e32 v60, v60
	v_exp_f32_e32 v61, v61
	v_exp_f32_e32 v62, v62
	v_exp_f32_e32 v63, v63
	v_exp_f32_e32 v56, v56
	v_exp_f32_e32 v57, v57
	v_exp_f32_e32 v58, v58
	v_exp_f32_e32 v59, v59
	v_pk_add_f32 v[60:61], v[60:61], v[188:189]
	v_pk_add_f32 v[62:63], v[62:63], v[188:189]
	v_pk_add_f32 v[56:57], v[56:57], v[188:189]
	v_pk_add_f32 v[58:59], v[58:59], v[188:189]
	v_rcp_f32_e32 v60, v60
	v_rcp_f32_e32 v61, v61
	v_rcp_f32_e32 v62, v62
	v_rcp_f32_e32 v63, v63
	v_rcp_f32_e32 v56, v56
	v_rcp_f32_e32 v57, v57
	v_rcp_f32_e32 v58, v58
	v_rcp_f32_e32 v59, v59
	s_waitcnt vmcnt(14)
	v_permlane16_swap_b32_e32 v200, v202
	v_permlane16_swap_b32_e32 v201, v203
	v_permlane16_swap_b32_e32 v204, v206
	v_permlane16_swap_b32_e32 v205, v207
	v_lshlrev_b32_e32 v168, 16, v200
	v_and_b32_e32 v169, 0xffff0000, v200
	v_lshlrev_b32_e32 v200, 16, v201
	v_and_b32_e32 v201, 0xffff0000, v201
	v_lshlrev_b32_e32 v170, 16, v202
	v_and_b32_e32 v171, 0xffff0000, v202
	v_lshlrev_b32_e32 v202, 16, v203
	v_and_b32_e32 v203, 0xffff0000, v203
	v_lshlrev_b32_e32 v172, 16, v204
	v_and_b32_e32 v173, 0xffff0000, v204
	v_lshlrev_b32_e32 v204, 16, v205
	v_and_b32_e32 v205, 0xffff0000, v205
	v_lshlrev_b32_e32 v174, 16, v206
	v_and_b32_e32 v175, 0xffff0000, v206
	v_lshlrev_b32_e32 v206, 16, v207
	v_and_b32_e32 v207, 0xffff0000, v207
	v_pk_fma_f32 v[124:125], v[124:125], v[172:173], v[168:169]
	v_pk_fma_f32 v[126:127], v[126:127], v[204:205], v[200:201]
	v_pk_fma_f32 v[120:121], v[120:121], v[174:175], v[170:171]
	v_pk_fma_f32 v[122:123], v[122:123], v[206:207], v[202:203]
	v_mov_b32_e32 v185, v184
	v_add_u32_e32 v192, 0x8000, v184
	v_mov_b32_e32 v172, v120
	v_mov_b32_e32 v173, v121
	v_mov_b32_e32 v174, v122
	v_mov_b32_e32 v175, v123
	v_mov_b32_dpp v120, v124 row_ror:8 row_mask:0xf bank_mask:0x3
	v_mov_b32_dpp v121, v125 row_ror:8 row_mask:0xf bank_mask:0x3
	v_mov_b32_dpp v122, v126 row_ror:8 row_mask:0xf bank_mask:0x3
	v_mov_b32_dpp v123, v127 row_ror:8 row_mask:0xf bank_mask:0x3
	v_mov_b32_dpp v124, v172 row_ror:8 row_mask:0xf bank_mask:0xc
	v_mov_b32_dpp v125, v173 row_ror:8 row_mask:0xf bank_mask:0xc
	v_mov_b32_dpp v126, v174 row_ror:8 row_mask:0xf bank_mask:0xc
	v_mov_b32_dpp v127, v175 row_ror:8 row_mask:0xf bank_mask:0xc
	global_store_dwordx4 v185, v[124:127], s[92:93]
	global_store_dwordx4 v192, v[120:123], s[92:93]
	global_load_dwordx4 v[200:203], v180, s[88:89]
	global_load_dwordx4 v[204:207], v180, s[4:5]
	v_pk_mul_f32 v[52:53], v[52:53], v[186:187]
	v_pk_mul_f32 v[54:55], v[54:55], v[186:187]
	v_pk_mul_f32 v[48:49], v[48:49], v[186:187]
	v_pk_mul_f32 v[50:51], v[50:51], v[186:187]
	v_exp_f32_e32 v52, v52
	v_exp_f32_e32 v53, v53
	v_exp_f32_e32 v54, v54
	v_exp_f32_e32 v55, v55
	v_exp_f32_e32 v48, v48
	v_exp_f32_e32 v49, v49
	v_exp_f32_e32 v50, v50
	v_exp_f32_e32 v51, v51
	v_pk_add_f32 v[52:53], v[52:53], v[188:189]
	v_pk_add_f32 v[54:55], v[54:55], v[188:189]
	v_pk_add_f32 v[48:49], v[48:49], v[188:189]
	v_pk_add_f32 v[50:51], v[50:51], v[188:189]
	v_rcp_f32_e32 v52, v52
	v_rcp_f32_e32 v53, v53
	v_rcp_f32_e32 v54, v54
	v_rcp_f32_e32 v55, v55
	v_rcp_f32_e32 v48, v48
	v_rcp_f32_e32 v49, v49
	v_rcp_f32_e32 v50, v50
	v_rcp_f32_e32 v51, v51
	s_waitcnt vmcnt(16)
	v_permlane16_swap_b32_e32 v208, v210
	v_permlane16_swap_b32_e32 v209, v211
	v_permlane16_swap_b32_e32 v212, v214
	v_permlane16_swap_b32_e32 v213, v215
	v_lshlrev_b32_e32 v168, 16, v208
	v_and_b32_e32 v169, 0xffff0000, v208
	v_lshlrev_b32_e32 v208, 16, v209
	v_and_b32_e32 v209, 0xffff0000, v209
	v_lshlrev_b32_e32 v170, 16, v210
	v_and_b32_e32 v171, 0xffff0000, v210
	v_lshlrev_b32_e32 v210, 16, v211
	v_and_b32_e32 v211, 0xffff0000, v211
	v_lshlrev_b32_e32 v172, 16, v212
	v_and_b32_e32 v173, 0xffff0000, v212
	v_lshlrev_b32_e32 v212, 16, v213
	v_and_b32_e32 v213, 0xffff0000, v213
	v_lshlrev_b32_e32 v174, 16, v214
	v_and_b32_e32 v175, 0xffff0000, v214
	v_lshlrev_b32_e32 v214, 16, v215
	v_and_b32_e32 v215, 0xffff0000, v215
	v_pk_fma_f32 v[116:117], v[116:117], v[172:173], v[168:169]
	v_pk_fma_f32 v[118:119], v[118:119], v[212:213], v[208:209]
	v_pk_fma_f32 v[112:113], v[112:113], v[174:175], v[170:171]
	v_pk_fma_f32 v[114:115], v[114:115], v[214:215], v[210:211]
	v_mov_b32_e32 v172, v112
	v_mov_b32_e32 v173, v113
	v_mov_b32_e32 v174, v114
	v_mov_b32_e32 v175, v115
	v_mov_b32_dpp v112, v116 row_ror:8 row_mask:0xf bank_mask:0x3
	v_mov_b32_dpp v113, v117 row_ror:8 row_mask:0xf bank_mask:0x3
	v_mov_b32_dpp v114, v118 row_ror:8 row_mask:0xf bank_mask:0x3
	v_mov_b32_dpp v115, v119 row_ror:8 row_mask:0xf bank_mask:0x3
	v_mov_b32_dpp v116, v172 row_ror:8 row_mask:0xf bank_mask:0xc
	v_mov_b32_dpp v117, v173 row_ror:8 row_mask:0xf bank_mask:0xc
	v_mov_b32_dpp v118, v174 row_ror:8 row_mask:0xf bank_mask:0xc
	v_mov_b32_dpp v119, v175 row_ror:8 row_mask:0xf bank_mask:0xc
	global_store_dwordx4 v185, v[116:119], s[92:93] offset:512
	global_store_dwordx4 v192, v[112:115], s[92:93] offset:512
	global_load_dwordx4 v[208:211], v180, s[88:89] offset:256
	global_load_dwordx4 v[212:215], v180, s[4:5] offset:256
	v_pk_mul_f32 v[44:45], v[44:45], v[186:187]
	v_pk_mul_f32 v[46:47], v[46:47], v[186:187]
	v_pk_mul_f32 v[40:41], v[40:41], v[186:187]
	v_pk_mul_f32 v[42:43], v[42:43], v[186:187]
	v_exp_f32_e32 v44, v44
	v_exp_f32_e32 v45, v45
	v_exp_f32_e32 v46, v46
	v_exp_f32_e32 v47, v47
	v_exp_f32_e32 v40, v40
	v_exp_f32_e32 v41, v41
	v_exp_f32_e32 v42, v42
	v_exp_f32_e32 v43, v43
	v_pk_add_f32 v[44:45], v[44:45], v[188:189]
	v_pk_add_f32 v[46:47], v[46:47], v[188:189]
	v_pk_add_f32 v[40:41], v[40:41], v[188:189]
	v_pk_add_f32 v[42:43], v[42:43], v[188:189]
	v_rcp_f32_e32 v44, v44
	v_rcp_f32_e32 v45, v45
	v_rcp_f32_e32 v46, v46
	v_rcp_f32_e32 v47, v47
	v_rcp_f32_e32 v40, v40
	v_rcp_f32_e32 v41, v41
	v_rcp_f32_e32 v42, v42
	v_rcp_f32_e32 v43, v43
	s_waitcnt vmcnt(18)
	v_permlane16_swap_b32_e32 v216, v218
	v_permlane16_swap_b32_e32 v217, v219
	v_permlane16_swap_b32_e32 v220, v222
	v_permlane16_swap_b32_e32 v221, v223
	v_lshlrev_b32_e32 v168, 16, v216
	v_and_b32_e32 v169, 0xffff0000, v216
	v_lshlrev_b32_e32 v216, 16, v217
	v_and_b32_e32 v217, 0xffff0000, v217
	v_lshlrev_b32_e32 v170, 16, v218
	v_and_b32_e32 v171, 0xffff0000, v218
	v_lshlrev_b32_e32 v218, 16, v219
	v_and_b32_e32 v219, 0xffff0000, v219
	v_lshlrev_b32_e32 v172, 16, v220
	v_and_b32_e32 v173, 0xffff0000, v220
	v_lshlrev_b32_e32 v220, 16, v221
	v_and_b32_e32 v221, 0xffff0000, v221
	v_lshlrev_b32_e32 v174, 16, v222
	v_and_b32_e32 v175, 0xffff0000, v222
	v_lshlrev_b32_e32 v222, 16, v223
	v_and_b32_e32 v223, 0xffff0000, v223
	v_pk_fma_f32 v[108:109], v[108:109], v[172:173], v[168:169]
	v_pk_fma_f32 v[110:111], v[110:111], v[220:221], v[216:217]
	v_pk_fma_f32 v[104:105], v[104:105], v[174:175], v[170:171]
	v_pk_fma_f32 v[106:107], v[106:107], v[222:223], v[218:219]
	v_add_u32_e32 v185, 0x10000, v184
	v_add_u32_e32 v192, 0x18000, v184
	v_mov_b32_e32 v172, v104
	v_mov_b32_e32 v173, v105
	v_mov_b32_e32 v174, v106
	v_mov_b32_e32 v175, v107
	v_mov_b32_dpp v104, v108 row_ror:8 row_mask:0xf bank_mask:0x3
	v_mov_b32_dpp v105, v109 row_ror:8 row_mask:0xf bank_mask:0x3
	v_mov_b32_dpp v106, v110 row_ror:8 row_mask:0xf bank_mask:0x3
	v_mov_b32_dpp v107, v111 row_ror:8 row_mask:0xf bank_mask:0x3
	v_mov_b32_dpp v108, v172 row_ror:8 row_mask:0xf bank_mask:0xc
	v_mov_b32_dpp v109, v173 row_ror:8 row_mask:0xf bank_mask:0xc
	v_mov_b32_dpp v110, v174 row_ror:8 row_mask:0xf bank_mask:0xc
	v_mov_b32_dpp v111, v175 row_ror:8 row_mask:0xf bank_mask:0xc
	global_store_dwordx4 v185, v[108:111], s[92:93]
	global_store_dwordx4 v192, v[104:107], s[92:93]
	global_load_dwordx4 v[216:219], v181, s[88:89]
	global_load_dwordx4 v[220:223], v181, s[4:5]
	v_pk_mul_f32 v[36:37], v[36:37], v[186:187]
	v_pk_mul_f32 v[38:39], v[38:39], v[186:187]
	v_pk_mul_f32 v[32:33], v[32:33], v[186:187]
	v_pk_mul_f32 v[34:35], v[34:35], v[186:187]
	v_exp_f32_e32 v36, v36
	v_exp_f32_e32 v37, v37
	v_exp_f32_e32 v38, v38
	v_exp_f32_e32 v39, v39
	v_exp_f32_e32 v32, v32
	v_exp_f32_e32 v33, v33
	v_exp_f32_e32 v34, v34
	v_exp_f32_e32 v35, v35
	v_pk_add_f32 v[36:37], v[36:37], v[188:189]
	v_pk_add_f32 v[38:39], v[38:39], v[188:189]
	v_pk_add_f32 v[32:33], v[32:33], v[188:189]
	v_pk_add_f32 v[34:35], v[34:35], v[188:189]
	v_rcp_f32_e32 v36, v36
	v_rcp_f32_e32 v37, v37
	v_rcp_f32_e32 v38, v38
	v_rcp_f32_e32 v39, v39
	v_rcp_f32_e32 v32, v32
	v_rcp_f32_e32 v33, v33
	v_rcp_f32_e32 v34, v34
	v_rcp_f32_e32 v35, v35
	s_waitcnt vmcnt(20)
	v_permlane16_swap_b32_e32 v224, v226
	v_permlane16_swap_b32_e32 v225, v227
	v_permlane16_swap_b32_e32 v228, v230
	v_permlane16_swap_b32_e32 v229, v231
	v_lshlrev_b32_e32 v168, 16, v224
	v_and_b32_e32 v169, 0xffff0000, v224
	v_lshlrev_b32_e32 v224, 16, v225
	v_and_b32_e32 v225, 0xffff0000, v225
	v_lshlrev_b32_e32 v170, 16, v226
	v_and_b32_e32 v171, 0xffff0000, v226
	v_lshlrev_b32_e32 v226, 16, v227
	v_and_b32_e32 v227, 0xffff0000, v227
	v_lshlrev_b32_e32 v172, 16, v228
	v_and_b32_e32 v173, 0xffff0000, v228
	v_lshlrev_b32_e32 v228, 16, v229
	v_and_b32_e32 v229, 0xffff0000, v229
	v_lshlrev_b32_e32 v174, 16, v230
	v_and_b32_e32 v175, 0xffff0000, v230
	v_lshlrev_b32_e32 v230, 16, v231
	v_and_b32_e32 v231, 0xffff0000, v231
	v_pk_fma_f32 v[100:101], v[100:101], v[172:173], v[168:169]
	v_pk_fma_f32 v[102:103], v[102:103], v[228:229], v[224:225]
	v_pk_fma_f32 v[96:97], v[96:97], v[174:175], v[170:171]
	v_pk_fma_f32 v[98:99], v[98:99], v[230:231], v[226:227]
	v_mov_b32_e32 v172, v96
	v_mov_b32_e32 v173, v97
	v_mov_b32_e32 v174, v98
	v_mov_b32_e32 v175, v99
	v_mov_b32_dpp v96, v100 row_ror:8 row_mask:0xf bank_mask:0x3
	v_mov_b32_dpp v97, v101 row_ror:8 row_mask:0xf bank_mask:0x3
	v_mov_b32_dpp v98, v102 row_ror:8 row_mask:0xf bank_mask:0x3
	v_mov_b32_dpp v99, v103 row_ror:8 row_mask:0xf bank_mask:0x3
	v_mov_b32_dpp v100, v172 row_ror:8 row_mask:0xf bank_mask:0xc
	v_mov_b32_dpp v101, v173 row_ror:8 row_mask:0xf bank_mask:0xc
	v_mov_b32_dpp v102, v174 row_ror:8 row_mask:0xf bank_mask:0xc
	v_mov_b32_dpp v103, v175 row_ror:8 row_mask:0xf bank_mask:0xc
	global_store_dwordx4 v185, v[100:103], s[92:93] offset:512
	global_store_dwordx4 v192, v[96:99], s[92:93] offset:512
	global_load_dwordx4 v[224:227], v181, s[88:89] offset:256
	global_load_dwordx4 v[228:231], v181, s[4:5] offset:256
	v_pk_mul_f32 v[28:29], v[28:29], v[186:187]
	v_pk_mul_f32 v[30:31], v[30:31], v[186:187]
	v_pk_mul_f32 v[24:25], v[24:25], v[186:187]
	v_pk_mul_f32 v[26:27], v[26:27], v[186:187]
	v_exp_f32_e32 v28, v28
	v_exp_f32_e32 v29, v29
	v_exp_f32_e32 v30, v30
	v_exp_f32_e32 v31, v31
	v_exp_f32_e32 v24, v24
	v_exp_f32_e32 v25, v25
	v_exp_f32_e32 v26, v26
	v_exp_f32_e32 v27, v27
	v_pk_add_f32 v[28:29], v[28:29], v[188:189]
	v_pk_add_f32 v[30:31], v[30:31], v[188:189]
	v_pk_add_f32 v[24:25], v[24:25], v[188:189]
	v_pk_add_f32 v[26:27], v[26:27], v[188:189]
	v_rcp_f32_e32 v28, v28
	v_rcp_f32_e32 v29, v29
	v_rcp_f32_e32 v30, v30
	v_rcp_f32_e32 v31, v31
	v_rcp_f32_e32 v24, v24
	v_rcp_f32_e32 v25, v25
	v_rcp_f32_e32 v26, v26
	v_rcp_f32_e32 v27, v27
	s_waitcnt vmcnt(22)
	v_permlane16_swap_b32_e32 v232, v234
	v_permlane16_swap_b32_e32 v233, v235
	v_permlane16_swap_b32_e32 v236, v238
	v_permlane16_swap_b32_e32 v237, v239
	v_lshlrev_b32_e32 v168, 16, v232
	v_and_b32_e32 v169, 0xffff0000, v232
	v_lshlrev_b32_e32 v232, 16, v233
	v_and_b32_e32 v233, 0xffff0000, v233
	v_lshlrev_b32_e32 v170, 16, v234
	v_and_b32_e32 v171, 0xffff0000, v234
	v_lshlrev_b32_e32 v234, 16, v235
	v_and_b32_e32 v235, 0xffff0000, v235
	v_lshlrev_b32_e32 v172, 16, v236
	v_and_b32_e32 v173, 0xffff0000, v236
	v_lshlrev_b32_e32 v236, 16, v237
	v_and_b32_e32 v237, 0xffff0000, v237
	v_lshlrev_b32_e32 v174, 16, v238
	v_and_b32_e32 v175, 0xffff0000, v238
	v_lshlrev_b32_e32 v238, 16, v239
	v_and_b32_e32 v239, 0xffff0000, v239
	v_pk_fma_f32 v[92:93], v[92:93], v[172:173], v[168:169]
	v_pk_fma_f32 v[94:95], v[94:95], v[236:237], v[232:233]
	v_pk_fma_f32 v[88:89], v[88:89], v[174:175], v[170:171]
	v_pk_fma_f32 v[90:91], v[90:91], v[238:239], v[234:235]
	v_add_u32_e32 v185, 0x20000, v184
	v_add_u32_e32 v192, 0x28000, v184
	v_mov_b32_e32 v172, v88
	v_mov_b32_e32 v173, v89
	v_mov_b32_e32 v174, v90
	v_mov_b32_e32 v175, v91
	v_mov_b32_dpp v88, v92 row_ror:8 row_mask:0xf bank_mask:0x3
	v_mov_b32_dpp v89, v93 row_ror:8 row_mask:0xf bank_mask:0x3
	v_mov_b32_dpp v90, v94 row_ror:8 row_mask:0xf bank_mask:0x3
	v_mov_b32_dpp v91, v95 row_ror:8 row_mask:0xf bank_mask:0x3
	v_mov_b32_dpp v92, v172 row_ror:8 row_mask:0xf bank_mask:0xc
	v_mov_b32_dpp v93, v173 row_ror:8 row_mask:0xf bank_mask:0xc
	v_mov_b32_dpp v94, v174 row_ror:8 row_mask:0xf bank_mask:0xc
	v_mov_b32_dpp v95, v175 row_ror:8 row_mask:0xf bank_mask:0xc
	global_store_dwordx4 v185, v[92:95], s[92:93]
	global_store_dwordx4 v192, v[88:91], s[92:93]
	global_load_dwordx4 v[232:235], v182, s[88:89]
	global_load_dwordx4 v[236:239], v182, s[4:5]
	v_pk_mul_f32 v[20:21], v[20:21], v[186:187]
	v_pk_mul_f32 v[22:23], v[22:23], v[186:187]
	v_pk_mul_f32 v[16:17], v[16:17], v[186:187]
	v_pk_mul_f32 v[18:19], v[18:19], v[186:187]
	v_exp_f32_e32 v20, v20
	v_exp_f32_e32 v21, v21
	v_exp_f32_e32 v22, v22
	v_exp_f32_e32 v23, v23
	v_exp_f32_e32 v16, v16
	v_exp_f32_e32 v17, v17
	v_exp_f32_e32 v18, v18
	v_exp_f32_e32 v19, v19
	v_pk_add_f32 v[20:21], v[20:21], v[188:189]
	v_pk_add_f32 v[22:23], v[22:23], v[188:189]
	v_pk_add_f32 v[16:17], v[16:17], v[188:189]
	v_pk_add_f32 v[18:19], v[18:19], v[188:189]
	v_rcp_f32_e32 v20, v20
	v_rcp_f32_e32 v21, v21
	v_rcp_f32_e32 v22, v22
	v_rcp_f32_e32 v23, v23
	v_rcp_f32_e32 v16, v16
	v_rcp_f32_e32 v17, v17
	v_rcp_f32_e32 v18, v18
	v_rcp_f32_e32 v19, v19
	s_waitcnt vmcnt(24)
	v_permlane16_swap_b32_e32 v240, v242
	v_permlane16_swap_b32_e32 v241, v243
	v_permlane16_swap_b32_e32 v244, v246
	v_permlane16_swap_b32_e32 v245, v247
	v_lshlrev_b32_e32 v168, 16, v240
	v_and_b32_e32 v169, 0xffff0000, v240
	v_lshlrev_b32_e32 v240, 16, v241
	v_and_b32_e32 v241, 0xffff0000, v241
	v_lshlrev_b32_e32 v170, 16, v242
	v_and_b32_e32 v171, 0xffff0000, v242
	v_lshlrev_b32_e32 v242, 16, v243
	v_and_b32_e32 v243, 0xffff0000, v243
	v_lshlrev_b32_e32 v172, 16, v244
	v_and_b32_e32 v173, 0xffff0000, v244
	v_lshlrev_b32_e32 v244, 16, v245
	v_and_b32_e32 v245, 0xffff0000, v245
	v_lshlrev_b32_e32 v174, 16, v246
	v_and_b32_e32 v175, 0xffff0000, v246
	v_lshlrev_b32_e32 v246, 16, v247
	v_and_b32_e32 v247, 0xffff0000, v247
	v_pk_fma_f32 v[84:85], v[84:85], v[172:173], v[168:169]
	v_pk_fma_f32 v[86:87], v[86:87], v[244:245], v[240:241]
	v_pk_fma_f32 v[80:81], v[80:81], v[174:175], v[170:171]
	v_pk_fma_f32 v[82:83], v[82:83], v[246:247], v[242:243]
	v_mov_b32_e32 v172, v80
	v_mov_b32_e32 v173, v81
	v_mov_b32_e32 v174, v82
	v_mov_b32_e32 v175, v83
	v_mov_b32_dpp v80, v84 row_ror:8 row_mask:0xf bank_mask:0x3
	v_mov_b32_dpp v81, v85 row_ror:8 row_mask:0xf bank_mask:0x3
	v_mov_b32_dpp v82, v86 row_ror:8 row_mask:0xf bank_mask:0x3
	v_mov_b32_dpp v83, v87 row_ror:8 row_mask:0xf bank_mask:0x3
	v_mov_b32_dpp v84, v172 row_ror:8 row_mask:0xf bank_mask:0xc
	v_mov_b32_dpp v85, v173 row_ror:8 row_mask:0xf bank_mask:0xc
	v_mov_b32_dpp v86, v174 row_ror:8 row_mask:0xf bank_mask:0xc
	v_mov_b32_dpp v87, v175 row_ror:8 row_mask:0xf bank_mask:0xc
	global_store_dwordx4 v185, v[84:87], s[92:93] offset:512
	global_store_dwordx4 v192, v[80:83], s[92:93] offset:512
	global_load_dwordx4 v[240:243], v182, s[88:89] offset:256
	global_load_dwordx4 v[244:247], v182, s[4:5] offset:256
	v_pk_mul_f32 v[12:13], v[12:13], v[186:187]
	v_pk_mul_f32 v[14:15], v[14:15], v[186:187]
	v_pk_mul_f32 v[8:9], v[8:9], v[186:187]
	v_pk_mul_f32 v[10:11], v[10:11], v[186:187]
	v_exp_f32_e32 v12, v12
	v_exp_f32_e32 v13, v13
	v_exp_f32_e32 v14, v14
	v_exp_f32_e32 v15, v15
	v_exp_f32_e32 v8, v8
	v_exp_f32_e32 v9, v9
	v_exp_f32_e32 v10, v10
	v_exp_f32_e32 v11, v11
	v_pk_add_f32 v[12:13], v[12:13], v[188:189]
	v_pk_add_f32 v[14:15], v[14:15], v[188:189]
	v_pk_add_f32 v[8:9], v[8:9], v[188:189]
	v_pk_add_f32 v[10:11], v[10:11], v[188:189]
	v_rcp_f32_e32 v12, v12
	v_rcp_f32_e32 v13, v13
	v_rcp_f32_e32 v14, v14
	v_rcp_f32_e32 v15, v15
	v_rcp_f32_e32 v8, v8
	v_rcp_f32_e32 v9, v9
	v_rcp_f32_e32 v10, v10
	v_rcp_f32_e32 v11, v11
	s_waitcnt vmcnt(26)
	v_permlane16_swap_b32_e32 v152, v154
	v_permlane16_swap_b32_e32 v153, v155
	v_permlane16_swap_b32_e32 v156, v158
	v_permlane16_swap_b32_e32 v157, v159
	v_lshlrev_b32_e32 v168, 16, v152
	v_and_b32_e32 v169, 0xffff0000, v152
	v_lshlrev_b32_e32 v152, 16, v153
	v_and_b32_e32 v153, 0xffff0000, v153
	v_lshlrev_b32_e32 v170, 16, v154
	v_and_b32_e32 v171, 0xffff0000, v154
	v_lshlrev_b32_e32 v154, 16, v155
	v_and_b32_e32 v155, 0xffff0000, v155
	v_lshlrev_b32_e32 v172, 16, v156
	v_and_b32_e32 v173, 0xffff0000, v156
	v_lshlrev_b32_e32 v156, 16, v157
	v_and_b32_e32 v157, 0xffff0000, v157
	v_lshlrev_b32_e32 v174, 16, v158
	v_and_b32_e32 v175, 0xffff0000, v158
	v_lshlrev_b32_e32 v158, 16, v159
	v_and_b32_e32 v159, 0xffff0000, v159
	v_pk_fma_f32 v[76:77], v[76:77], v[172:173], v[168:169]
	v_pk_fma_f32 v[78:79], v[78:79], v[156:157], v[152:153]
	v_pk_fma_f32 v[72:73], v[72:73], v[174:175], v[170:171]
	v_pk_fma_f32 v[74:75], v[74:75], v[158:159], v[154:155]
	v_add_u32_e32 v185, 0x30000, v184
	v_add_u32_e32 v192, 0x38000, v184
	v_mov_b32_e32 v172, v72
	v_mov_b32_e32 v173, v73
	v_mov_b32_e32 v174, v74
	v_mov_b32_e32 v175, v75
	v_mov_b32_dpp v72, v76 row_ror:8 row_mask:0xf bank_mask:0x3
	v_mov_b32_dpp v73, v77 row_ror:8 row_mask:0xf bank_mask:0x3
	v_mov_b32_dpp v74, v78 row_ror:8 row_mask:0xf bank_mask:0x3
	v_mov_b32_dpp v75, v79 row_ror:8 row_mask:0xf bank_mask:0x3
	v_mov_b32_dpp v76, v172 row_ror:8 row_mask:0xf bank_mask:0xc
	v_mov_b32_dpp v77, v173 row_ror:8 row_mask:0xf bank_mask:0xc
	v_mov_b32_dpp v78, v174 row_ror:8 row_mask:0xf bank_mask:0xc
	v_mov_b32_dpp v79, v175 row_ror:8 row_mask:0xf bank_mask:0xc
	global_store_dwordx4 v185, v[76:79], s[92:93]
	global_store_dwordx4 v192, v[72:75], s[92:93]
	global_load_dwordx4 v[152:155], v183, s[88:89]
	global_load_dwordx4 v[156:159], v183, s[4:5]
	v_pk_mul_f32 v[4:5], v[4:5], v[186:187]
	v_pk_mul_f32 v[6:7], v[6:7], v[186:187]
	v_pk_mul_f32 v[0:1], v[0:1], v[186:187]
	v_pk_mul_f32 v[2:3], v[2:3], v[186:187]
	v_exp_f32_e32 v4, v4
	v_exp_f32_e32 v5, v5
	v_exp_f32_e32 v6, v6
	v_exp_f32_e32 v7, v7
	v_exp_f32_e32 v0, v0
	v_exp_f32_e32 v1, v1
	v_exp_f32_e32 v2, v2
	v_exp_f32_e32 v3, v3
	v_pk_add_f32 v[4:5], v[4:5], v[188:189]
	v_pk_add_f32 v[6:7], v[6:7], v[188:189]
	v_pk_add_f32 v[0:1], v[0:1], v[188:189]
	v_pk_add_f32 v[2:3], v[2:3], v[188:189]
	v_rcp_f32_e32 v4, v4
	v_rcp_f32_e32 v5, v5
	v_rcp_f32_e32 v6, v6
	v_rcp_f32_e32 v7, v7
	v_rcp_f32_e32 v0, v0
	v_rcp_f32_e32 v1, v1
	v_rcp_f32_e32 v2, v2
	v_rcp_f32_e32 v3, v3
	s_waitcnt vmcnt(28)
	v_permlane16_swap_b32_e32 v160, v162
	v_permlane16_swap_b32_e32 v161, v163
	v_permlane16_swap_b32_e32 v164, v166
	v_permlane16_swap_b32_e32 v165, v167
	v_lshlrev_b32_e32 v168, 16, v160
	v_and_b32_e32 v169, 0xffff0000, v160
	v_lshlrev_b32_e32 v160, 16, v161
	v_and_b32_e32 v161, 0xffff0000, v161
	v_lshlrev_b32_e32 v170, 16, v162
	v_and_b32_e32 v171, 0xffff0000, v162
	v_lshlrev_b32_e32 v162, 16, v163
	v_and_b32_e32 v163, 0xffff0000, v163
	v_lshlrev_b32_e32 v172, 16, v164
	v_and_b32_e32 v173, 0xffff0000, v164
	v_lshlrev_b32_e32 v164, 16, v165
	v_and_b32_e32 v165, 0xffff0000, v165
	v_lshlrev_b32_e32 v174, 16, v166
	v_and_b32_e32 v175, 0xffff0000, v166
	v_lshlrev_b32_e32 v166, 16, v167
	v_and_b32_e32 v167, 0xffff0000, v167
	v_pk_fma_f32 v[68:69], v[68:69], v[172:173], v[168:169]
	v_pk_fma_f32 v[70:71], v[70:71], v[164:165], v[160:161]
	v_pk_fma_f32 v[64:65], v[64:65], v[174:175], v[170:171]
	v_pk_fma_f32 v[66:67], v[66:67], v[166:167], v[162:163]
	v_mov_b32_e32 v172, v64
	v_mov_b32_e32 v173, v65
	v_mov_b32_e32 v174, v66
	v_mov_b32_e32 v175, v67
	v_mov_b32_dpp v64, v68 row_ror:8 row_mask:0xf bank_mask:0x3
	v_mov_b32_dpp v65, v69 row_ror:8 row_mask:0xf bank_mask:0x3
	v_mov_b32_dpp v66, v70 row_ror:8 row_mask:0xf bank_mask:0x3
	v_mov_b32_dpp v67, v71 row_ror:8 row_mask:0xf bank_mask:0x3
	v_mov_b32_dpp v68, v172 row_ror:8 row_mask:0xf bank_mask:0xc
	v_mov_b32_dpp v69, v173 row_ror:8 row_mask:0xf bank_mask:0xc
	v_mov_b32_dpp v70, v174 row_ror:8 row_mask:0xf bank_mask:0xc
	v_mov_b32_dpp v71, v175 row_ror:8 row_mask:0xf bank_mask:0xc
	global_store_dwordx4 v185, v[68:71], s[92:93] offset:512
	global_store_dwordx4 v192, v[64:67], s[92:93] offset:512
	global_load_dwordx4 v[160:163], v183, s[88:89] offset:256
	global_load_dwordx4 v[164:167], v183, s[4:5] offset:256
	s_mov_b32 s33, s16
	s_mov_b32 s24, s18
	s_mov_b64 s[28:29], s[22:23]
	s_mov_b64 s[26:27], s[20:21]
	s_waitcnt vmcnt(28)
	v_permlane16_swap_b32_e32 v200, v202
	v_permlane16_swap_b32_e32 v201, v203
	v_permlane16_swap_b32_e32 v204, v206
	v_permlane16_swap_b32_e32 v205, v207
	v_lshlrev_b32_e32 v168, 16, v200
	v_and_b32_e32 v169, 0xffff0000, v200
	v_lshlrev_b32_e32 v200, 16, v201
	v_and_b32_e32 v201, 0xffff0000, v201
	v_lshlrev_b32_e32 v170, 16, v202
	v_and_b32_e32 v171, 0xffff0000, v202
	v_lshlrev_b32_e32 v202, 16, v203
	v_and_b32_e32 v203, 0xffff0000, v203
	v_lshlrev_b32_e32 v172, 16, v204
	v_and_b32_e32 v173, 0xffff0000, v204
	v_lshlrev_b32_e32 v204, 16, v205
	v_and_b32_e32 v205, 0xffff0000, v205
	v_lshlrev_b32_e32 v174, 16, v206
	v_and_b32_e32 v175, 0xffff0000, v206
	v_lshlrev_b32_e32 v206, 16, v207
	v_and_b32_e32 v207, 0xffff0000, v207
	v_pk_fma_f32 v[60:61], v[60:61], v[172:173], v[168:169]
	v_pk_fma_f32 v[62:63], v[62:63], v[204:205], v[200:201]
	v_pk_fma_f32 v[56:57], v[56:57], v[174:175], v[170:171]
	v_pk_fma_f32 v[58:59], v[58:59], v[206:207], v[202:203]
	v_add_u32_e32 v185, 0x80000, v184
	v_add_u32_e32 v192, 0x88000, v184
	v_mov_b32_e32 v172, v56
	v_mov_b32_e32 v173, v57
	v_mov_b32_e32 v174, v58
	v_mov_b32_e32 v175, v59
	v_mov_b32_dpp v56, v60 row_ror:8 row_mask:0xf bank_mask:0x3
	v_mov_b32_dpp v57, v61 row_ror:8 row_mask:0xf bank_mask:0x3
	v_mov_b32_dpp v58, v62 row_ror:8 row_mask:0xf bank_mask:0x3
	v_mov_b32_dpp v59, v63 row_ror:8 row_mask:0xf bank_mask:0x3
	v_mov_b32_dpp v60, v172 row_ror:8 row_mask:0xf bank_mask:0xc
	v_mov_b32_dpp v61, v173 row_ror:8 row_mask:0xf bank_mask:0xc
	v_mov_b32_dpp v62, v174 row_ror:8 row_mask:0xf bank_mask:0xc
	v_mov_b32_dpp v63, v175 row_ror:8 row_mask:0xf bank_mask:0xc
	global_store_dwordx4 v185, v[60:63], s[92:93]
	global_store_dwordx4 v192, v[56:59], s[92:93]
	s_waitcnt vmcnt(26)
	v_permlane16_swap_b32_e32 v208, v210
	v_permlane16_swap_b32_e32 v209, v211
	v_permlane16_swap_b32_e32 v212, v214
	v_permlane16_swap_b32_e32 v213, v215
	v_lshlrev_b32_e32 v168, 16, v208
	v_and_b32_e32 v169, 0xffff0000, v208
	v_lshlrev_b32_e32 v208, 16, v209
	v_and_b32_e32 v209, 0xffff0000, v209
	v_lshlrev_b32_e32 v170, 16, v210
	v_and_b32_e32 v171, 0xffff0000, v210
	v_lshlrev_b32_e32 v210, 16, v211
	v_and_b32_e32 v211, 0xffff0000, v211
	v_lshlrev_b32_e32 v172, 16, v212
	v_and_b32_e32 v173, 0xffff0000, v212
	v_lshlrev_b32_e32 v212, 16, v213
	v_and_b32_e32 v213, 0xffff0000, v213
	v_lshlrev_b32_e32 v174, 16, v214
	v_and_b32_e32 v175, 0xffff0000, v214
	v_lshlrev_b32_e32 v214, 16, v215
	v_and_b32_e32 v215, 0xffff0000, v215
	v_pk_fma_f32 v[52:53], v[52:53], v[172:173], v[168:169]
	v_pk_fma_f32 v[54:55], v[54:55], v[212:213], v[208:209]
	v_pk_fma_f32 v[48:49], v[48:49], v[174:175], v[170:171]
	v_pk_fma_f32 v[50:51], v[50:51], v[214:215], v[210:211]
	v_mov_b32_e32 v172, v48
	v_mov_b32_e32 v173, v49
	v_mov_b32_e32 v174, v50
	v_mov_b32_e32 v175, v51
	v_mov_b32_dpp v48, v52 row_ror:8 row_mask:0xf bank_mask:0x3
	v_mov_b32_dpp v49, v53 row_ror:8 row_mask:0xf bank_mask:0x3
	v_mov_b32_dpp v50, v54 row_ror:8 row_mask:0xf bank_mask:0x3
	v_mov_b32_dpp v51, v55 row_ror:8 row_mask:0xf bank_mask:0x3
	v_mov_b32_dpp v52, v172 row_ror:8 row_mask:0xf bank_mask:0xc
	v_mov_b32_dpp v53, v173 row_ror:8 row_mask:0xf bank_mask:0xc
	v_mov_b32_dpp v54, v174 row_ror:8 row_mask:0xf bank_mask:0xc
	v_mov_b32_dpp v55, v175 row_ror:8 row_mask:0xf bank_mask:0xc
	global_store_dwordx4 v185, v[52:55], s[92:93] offset:512
	global_store_dwordx4 v192, v[48:51], s[92:93] offset:512
	s_waitcnt vmcnt(24)
	v_permlane16_swap_b32_e32 v216, v218
	v_permlane16_swap_b32_e32 v217, v219
	v_permlane16_swap_b32_e32 v220, v222
	v_permlane16_swap_b32_e32 v221, v223
	v_lshlrev_b32_e32 v168, 16, v216
	v_and_b32_e32 v169, 0xffff0000, v216
	v_lshlrev_b32_e32 v216, 16, v217
	v_and_b32_e32 v217, 0xffff0000, v217
	v_lshlrev_b32_e32 v170, 16, v218
	v_and_b32_e32 v171, 0xffff0000, v218
	v_lshlrev_b32_e32 v218, 16, v219
	v_and_b32_e32 v219, 0xffff0000, v219
	v_lshlrev_b32_e32 v172, 16, v220
	v_and_b32_e32 v173, 0xffff0000, v220
	v_lshlrev_b32_e32 v220, 16, v221
	v_and_b32_e32 v221, 0xffff0000, v221
	v_lshlrev_b32_e32 v174, 16, v222
	v_and_b32_e32 v175, 0xffff0000, v222
	v_lshlrev_b32_e32 v222, 16, v223
	v_and_b32_e32 v223, 0xffff0000, v223
	v_pk_fma_f32 v[44:45], v[44:45], v[172:173], v[168:169]
	v_pk_fma_f32 v[46:47], v[46:47], v[220:221], v[216:217]
	v_pk_fma_f32 v[40:41], v[40:41], v[174:175], v[170:171]
	v_pk_fma_f32 v[42:43], v[42:43], v[222:223], v[218:219]
	v_add_u32_e32 v185, 0x90000, v184
	v_add_u32_e32 v192, 0x98000, v184
	v_mov_b32_e32 v172, v40
	v_mov_b32_e32 v173, v41
	v_mov_b32_e32 v174, v42
	v_mov_b32_e32 v175, v43
	v_mov_b32_dpp v40, v44 row_ror:8 row_mask:0xf bank_mask:0x3
	v_mov_b32_dpp v41, v45 row_ror:8 row_mask:0xf bank_mask:0x3
	v_mov_b32_dpp v42, v46 row_ror:8 row_mask:0xf bank_mask:0x3
	v_mov_b32_dpp v43, v47 row_ror:8 row_mask:0xf bank_mask:0x3
	v_mov_b32_dpp v44, v172 row_ror:8 row_mask:0xf bank_mask:0xc
	v_mov_b32_dpp v45, v173 row_ror:8 row_mask:0xf bank_mask:0xc
	v_mov_b32_dpp v46, v174 row_ror:8 row_mask:0xf bank_mask:0xc
	v_mov_b32_dpp v47, v175 row_ror:8 row_mask:0xf bank_mask:0xc
	global_store_dwordx4 v185, v[44:47], s[92:93]
	global_store_dwordx4 v192, v[40:43], s[92:93]
	s_waitcnt vmcnt(22)
	v_permlane16_swap_b32_e32 v224, v226
	v_permlane16_swap_b32_e32 v225, v227
	v_permlane16_swap_b32_e32 v228, v230
	v_permlane16_swap_b32_e32 v229, v231
	v_lshlrev_b32_e32 v168, 16, v224
	v_and_b32_e32 v169, 0xffff0000, v224
	v_lshlrev_b32_e32 v224, 16, v225
	v_and_b32_e32 v225, 0xffff0000, v225
	v_lshlrev_b32_e32 v170, 16, v226
	v_and_b32_e32 v171, 0xffff0000, v226
	v_lshlrev_b32_e32 v226, 16, v227
	v_and_b32_e32 v227, 0xffff0000, v227
	v_lshlrev_b32_e32 v172, 16, v228
	v_and_b32_e32 v173, 0xffff0000, v228
	v_lshlrev_b32_e32 v228, 16, v229
	v_and_b32_e32 v229, 0xffff0000, v229
	v_lshlrev_b32_e32 v174, 16, v230
	v_and_b32_e32 v175, 0xffff0000, v230
	v_lshlrev_b32_e32 v230, 16, v231
	v_and_b32_e32 v231, 0xffff0000, v231
	v_pk_fma_f32 v[36:37], v[36:37], v[172:173], v[168:169]
	v_pk_fma_f32 v[38:39], v[38:39], v[228:229], v[224:225]
	v_pk_fma_f32 v[32:33], v[32:33], v[174:175], v[170:171]
	v_pk_fma_f32 v[34:35], v[34:35], v[230:231], v[226:227]
	v_mov_b32_e32 v172, v32
	v_mov_b32_e32 v173, v33
	v_mov_b32_e32 v174, v34
	v_mov_b32_e32 v175, v35
	v_mov_b32_dpp v32, v36 row_ror:8 row_mask:0xf bank_mask:0x3
	v_mov_b32_dpp v33, v37 row_ror:8 row_mask:0xf bank_mask:0x3
	v_mov_b32_dpp v34, v38 row_ror:8 row_mask:0xf bank_mask:0x3
	v_mov_b32_dpp v35, v39 row_ror:8 row_mask:0xf bank_mask:0x3
	v_mov_b32_dpp v36, v172 row_ror:8 row_mask:0xf bank_mask:0xc
	v_mov_b32_dpp v37, v173 row_ror:8 row_mask:0xf bank_mask:0xc
	v_mov_b32_dpp v38, v174 row_ror:8 row_mask:0xf bank_mask:0xc
	v_mov_b32_dpp v39, v175 row_ror:8 row_mask:0xf bank_mask:0xc
	global_store_dwordx4 v185, v[36:39], s[92:93] offset:512
	global_store_dwordx4 v192, v[32:35], s[92:93] offset:512
	s_waitcnt vmcnt(20)
	v_permlane16_swap_b32_e32 v232, v234
	v_permlane16_swap_b32_e32 v233, v235
	v_permlane16_swap_b32_e32 v236, v238
	v_permlane16_swap_b32_e32 v237, v239
	v_lshlrev_b32_e32 v168, 16, v232
	v_and_b32_e32 v169, 0xffff0000, v232
	v_lshlrev_b32_e32 v232, 16, v233
	v_and_b32_e32 v233, 0xffff0000, v233
	v_lshlrev_b32_e32 v170, 16, v234
	v_and_b32_e32 v171, 0xffff0000, v234
	v_lshlrev_b32_e32 v234, 16, v235
	v_and_b32_e32 v235, 0xffff0000, v235
	v_lshlrev_b32_e32 v172, 16, v236
	v_and_b32_e32 v173, 0xffff0000, v236
	v_lshlrev_b32_e32 v236, 16, v237
	v_and_b32_e32 v237, 0xffff0000, v237
	v_lshlrev_b32_e32 v174, 16, v238
	v_and_b32_e32 v175, 0xffff0000, v238
	v_lshlrev_b32_e32 v238, 16, v239
	v_and_b32_e32 v239, 0xffff0000, v239
	v_pk_fma_f32 v[28:29], v[28:29], v[172:173], v[168:169]
	v_pk_fma_f32 v[30:31], v[30:31], v[236:237], v[232:233]
	v_pk_fma_f32 v[24:25], v[24:25], v[174:175], v[170:171]
	v_pk_fma_f32 v[26:27], v[26:27], v[238:239], v[234:235]
	v_add_u32_e32 v185, 0xa0000, v184
	v_add_u32_e32 v192, 0xa8000, v184
	v_mov_b32_e32 v172, v24
	v_mov_b32_e32 v173, v25
	v_mov_b32_e32 v174, v26
	v_mov_b32_e32 v175, v27
	v_mov_b32_dpp v24, v28 row_ror:8 row_mask:0xf bank_mask:0x3
	v_mov_b32_dpp v25, v29 row_ror:8 row_mask:0xf bank_mask:0x3
	v_mov_b32_dpp v26, v30 row_ror:8 row_mask:0xf bank_mask:0x3
	v_mov_b32_dpp v27, v31 row_ror:8 row_mask:0xf bank_mask:0x3
	v_mov_b32_dpp v28, v172 row_ror:8 row_mask:0xf bank_mask:0xc
	v_mov_b32_dpp v29, v173 row_ror:8 row_mask:0xf bank_mask:0xc
	v_mov_b32_dpp v30, v174 row_ror:8 row_mask:0xf bank_mask:0xc
	v_mov_b32_dpp v31, v175 row_ror:8 row_mask:0xf bank_mask:0xc
	global_store_dwordx4 v185, v[28:31], s[92:93]
	global_store_dwordx4 v192, v[24:27], s[92:93]
	s_waitcnt vmcnt(18)
	v_permlane16_swap_b32_e32 v240, v242
	v_permlane16_swap_b32_e32 v241, v243
	v_permlane16_swap_b32_e32 v244, v246
	v_permlane16_swap_b32_e32 v245, v247
	v_lshlrev_b32_e32 v168, 16, v240
	v_and_b32_e32 v169, 0xffff0000, v240
	v_lshlrev_b32_e32 v240, 16, v241
	v_and_b32_e32 v241, 0xffff0000, v241
	v_lshlrev_b32_e32 v170, 16, v242
	v_and_b32_e32 v171, 0xffff0000, v242
	v_lshlrev_b32_e32 v242, 16, v243
	v_and_b32_e32 v243, 0xffff0000, v243
	v_lshlrev_b32_e32 v172, 16, v244
	v_and_b32_e32 v173, 0xffff0000, v244
	v_lshlrev_b32_e32 v244, 16, v245
	v_and_b32_e32 v245, 0xffff0000, v245
	v_lshlrev_b32_e32 v174, 16, v246
	v_and_b32_e32 v175, 0xffff0000, v246
	v_lshlrev_b32_e32 v246, 16, v247
	v_and_b32_e32 v247, 0xffff0000, v247
	v_pk_fma_f32 v[20:21], v[20:21], v[172:173], v[168:169]
	v_pk_fma_f32 v[22:23], v[22:23], v[244:245], v[240:241]
	v_pk_fma_f32 v[16:17], v[16:17], v[174:175], v[170:171]
	v_pk_fma_f32 v[18:19], v[18:19], v[246:247], v[242:243]
	v_mov_b32_e32 v172, v16
	v_mov_b32_e32 v173, v17
	v_mov_b32_e32 v174, v18
	v_mov_b32_e32 v175, v19
	v_mov_b32_dpp v16, v20 row_ror:8 row_mask:0xf bank_mask:0x3
	v_mov_b32_dpp v17, v21 row_ror:8 row_mask:0xf bank_mask:0x3
	v_mov_b32_dpp v18, v22 row_ror:8 row_mask:0xf bank_mask:0x3
	v_mov_b32_dpp v19, v23 row_ror:8 row_mask:0xf bank_mask:0x3
	v_mov_b32_dpp v20, v172 row_ror:8 row_mask:0xf bank_mask:0xc
	v_mov_b32_dpp v21, v173 row_ror:8 row_mask:0xf bank_mask:0xc
	v_mov_b32_dpp v22, v174 row_ror:8 row_mask:0xf bank_mask:0xc
	v_mov_b32_dpp v23, v175 row_ror:8 row_mask:0xf bank_mask:0xc
	global_store_dwordx4 v185, v[20:23], s[92:93] offset:512
	global_store_dwordx4 v192, v[16:19], s[92:93] offset:512
	s_waitcnt vmcnt(16)
	v_permlane16_swap_b32_e32 v152, v154
	v_permlane16_swap_b32_e32 v153, v155
	v_permlane16_swap_b32_e32 v156, v158
	v_permlane16_swap_b32_e32 v157, v159
	v_lshlrev_b32_e32 v168, 16, v152
	v_and_b32_e32 v169, 0xffff0000, v152
	v_lshlrev_b32_e32 v152, 16, v153
	v_and_b32_e32 v153, 0xffff0000, v153
	v_lshlrev_b32_e32 v170, 16, v154
	v_and_b32_e32 v171, 0xffff0000, v154
	v_lshlrev_b32_e32 v154, 16, v155
	v_and_b32_e32 v155, 0xffff0000, v155
	v_lshlrev_b32_e32 v172, 16, v156
	v_and_b32_e32 v173, 0xffff0000, v156
	v_lshlrev_b32_e32 v156, 16, v157
	v_and_b32_e32 v157, 0xffff0000, v157
	v_lshlrev_b32_e32 v174, 16, v158
	v_and_b32_e32 v175, 0xffff0000, v158
	v_lshlrev_b32_e32 v158, 16, v159
	v_and_b32_e32 v159, 0xffff0000, v159
	v_pk_fma_f32 v[12:13], v[12:13], v[172:173], v[168:169]
	v_pk_fma_f32 v[14:15], v[14:15], v[156:157], v[152:153]
	v_pk_fma_f32 v[8:9], v[8:9], v[174:175], v[170:171]
	v_pk_fma_f32 v[10:11], v[10:11], v[158:159], v[154:155]
	v_add_u32_e32 v185, 0xb0000, v184
	v_add_u32_e32 v192, 0xb8000, v184
	v_mov_b32_e32 v172, v8
	v_mov_b32_e32 v173, v9
	v_mov_b32_e32 v174, v10
	v_mov_b32_e32 v175, v11
	v_mov_b32_dpp v8, v12 row_ror:8 row_mask:0xf bank_mask:0x3
	v_mov_b32_dpp v9, v13 row_ror:8 row_mask:0xf bank_mask:0x3
	v_mov_b32_dpp v10, v14 row_ror:8 row_mask:0xf bank_mask:0x3
	v_mov_b32_dpp v11, v15 row_ror:8 row_mask:0xf bank_mask:0x3
	v_mov_b32_dpp v12, v172 row_ror:8 row_mask:0xf bank_mask:0xc
	v_mov_b32_dpp v13, v173 row_ror:8 row_mask:0xf bank_mask:0xc
	v_mov_b32_dpp v14, v174 row_ror:8 row_mask:0xf bank_mask:0xc
	v_mov_b32_dpp v15, v175 row_ror:8 row_mask:0xf bank_mask:0xc
	global_store_dwordx4 v185, v[12:15], s[92:93]
	global_store_dwordx4 v192, v[8:11], s[92:93]
	s_waitcnt vmcnt(14)
	v_permlane16_swap_b32_e32 v160, v162
	v_permlane16_swap_b32_e32 v161, v163
	v_permlane16_swap_b32_e32 v164, v166
	v_permlane16_swap_b32_e32 v165, v167
	v_lshlrev_b32_e32 v168, 16, v160
	v_and_b32_e32 v169, 0xffff0000, v160
	v_lshlrev_b32_e32 v160, 16, v161
	v_and_b32_e32 v161, 0xffff0000, v161
	v_lshlrev_b32_e32 v170, 16, v162
	v_and_b32_e32 v171, 0xffff0000, v162
	v_lshlrev_b32_e32 v162, 16, v163
	v_and_b32_e32 v163, 0xffff0000, v163
	v_lshlrev_b32_e32 v172, 16, v164
	v_and_b32_e32 v173, 0xffff0000, v164
	v_lshlrev_b32_e32 v164, 16, v165
	v_and_b32_e32 v165, 0xffff0000, v165
	v_lshlrev_b32_e32 v174, 16, v166
	v_and_b32_e32 v175, 0xffff0000, v166
	v_lshlrev_b32_e32 v166, 16, v167
	v_and_b32_e32 v167, 0xffff0000, v167
	v_pk_fma_f32 v[4:5], v[4:5], v[172:173], v[168:169]
	v_pk_fma_f32 v[6:7], v[6:7], v[164:165], v[160:161]
	v_pk_fma_f32 v[0:1], v[0:1], v[174:175], v[170:171]
	v_pk_fma_f32 v[2:3], v[2:3], v[166:167], v[162:163]
	v_mov_b32_e32 v172, v0
	v_mov_b32_e32 v173, v1
	v_mov_b32_e32 v174, v2
	v_mov_b32_e32 v175, v3
	v_mov_b32_dpp v0, v4 row_ror:8 row_mask:0xf bank_mask:0x3
	v_mov_b32_dpp v1, v5 row_ror:8 row_mask:0xf bank_mask:0x3
	v_mov_b32_dpp v2, v6 row_ror:8 row_mask:0xf bank_mask:0x3
	v_mov_b32_dpp v3, v7 row_ror:8 row_mask:0xf bank_mask:0x3
	v_mov_b32_dpp v4, v172 row_ror:8 row_mask:0xf bank_mask:0xc
	v_mov_b32_dpp v5, v173 row_ror:8 row_mask:0xf bank_mask:0xc
	v_mov_b32_dpp v6, v174 row_ror:8 row_mask:0xf bank_mask:0xc
	v_mov_b32_dpp v7, v175 row_ror:8 row_mask:0xf bank_mask:0xc
	global_store_dwordx4 v185, v[4:7], s[92:93] offset:512
	global_store_dwordx4 v192, v[0:3], s[92:93] offset:512
	s_cbranch_vccz .LBB0_1607
	s_waitcnt vmcnt(0)
	s_cmpk_gt_u32 s34, 0xff
	s_cbranch_scc1 .LBB0_1618
	s_barrier
